# attention: remap which 32-query slice each wave takes so the causal diagonal tiles are balanced across SIMD partner waves
# speedup vs baseline: 1.0028x; 1.0028x over previous
; __device__ __forceinline__ float bf_lo(unsigned w) { return __uint_as_float(w << 16); }
; template <int DQK, int DV, int MODE>
; __device__ __forceinline__ void attn_unit(LAS unsigned char* lds, const AttnP& P, size_t rowbase, int qb, const int tid, const int pm) {
;     ...
;     const int lane = tid & 63, wid = __builtin_amdgcn_readfirstlane(tid >> 6), r32 = lane & 31, hi = lane >> 5;
;     const int q0 = qb * 256, NT = 4 * qb + 4, ktlast = 4 * qb + (wid >> 1);
;     const int qpos = q0 + wid * 32 + r32;
;     bf16x8 qf[NKS];
;     {
;         const bf16_t* qrow = P.Q + (rowbase + qpos) * (size_t)P.ldq + hi * 8;
; #pragma unroll
;         for (int ks = 0; ks < NKS; ++ks) qf[ks] = *(const bf16x8*)(qrow + ks * 16);
;     }
;     float cq2 = 0.f;
;     if (MODE == 0) cq2 = P.bias[qpos];
;     float sdiag = 0.f;
;     {
;         const bf16_t* kd = P.K1 + (rowbase + qpos) * (size_t)P.ldk1 + hi * 8;
; #pragma unroll
;         for (int ks = 0; ks < NKS; ++ks) {
;             const u32x4 kv_ = (MODE == 1 && ks >= 4) ? *(const u32x4*)(P.K2 + (rowbase + qpos) * 32 + (ks - 4) * 16 + hi * 8) : *(const u32x4*)(kd + ks * 16);
;             const u32x4 qv_ = __builtin_bit_cast(u32x4, qf[ks]);
;             sdiag += bf_lo(qv_.x) * bf_lo(kv_.x) + bf_hi(qv_.x) * bf_hi(kv_.x) + bf_lo(qv_.y) * bf_lo(kv_.y) + bf_hi(qv_.y) * bf_hi(kv_.y)
;                    + bf_lo(qv_.z) * bf_lo(kv_.z) + bf_hi(qv_.z) * bf_hi(kv_.z) + bf_lo(qv_.w) * bf_lo(kv_.w) + bf_hi(qv_.w) * bf_hi(kv_.w);
;         }
;         auto rr_ = __builtin_amdgcn_permlane32_swap(__float_as_uint(sdiag), __float_as_uint(sdiag), false, false);
;         sdiag = __uint_as_float(rr_[0]) + __uint_as_float(rr_[1]);
;     }
;     u32x4 kA0, kA1, vA0, vA1, kB0, kB1, vB0, vB1; float bA = 0.f, bB = 0.f;
;     kA1 = (u32x4){0, 0, 0, 0}; vA1 = kA1; kB1 = kA1; vB1 = kA1;
;     const int krow = tid >> 3, kch = tid & 7, k2row = tid >> 2, k2ch = tid & 3;
;     const int vrow = (DV == 64) ? (tid >> 3) : (tid >> 4), vch = (DV == 64) ? (tid & 7) : (tid & 15);
;     const unsigned koff = (unsigned)(krow * P.ldk1 + kch * 8), k2off = (unsigned)(k2row * 32 + k2ch * 8), voff0 = (unsigned)(vrow * P.ldv + vch * 8), voff1 = voff0 + 32u * (unsigned)P.ldv;
;     ...
;     ATT_LOAD(A, 0); ATT_LOAD(B, 1);
;     ATT_STORE(A, 0); ATT_STORE(B, 1);
;     ATT_LOAD(A, 2); ATT_LOAD(B, 3);
;     ATT_BAR();
.LBB0_139:
	s_or_b32 s94, s26, s41
	s_xor_b64 s[22:23], s[24:25], -1
	s_lshl_b64 s[26:27], s[94:95], 1
	s_add_u32 s46, s0, s26
	s_addc_u32 s47, s1, s27
	s_add_u32 s28, s30, s26
	v_readfirstlane_b32 s45, v155
	s_addc_u32 s29, s31, s27
	s_lshr_b32 s44, s45, 6
	s_mul_i32 s44, s44, 3
	s_lshr_b32 s44, 0x54e8f8, s44
	s_and_b32 s44, s44, 7
	s_lshr_b32 s44, s44, 1
	s_lshr_b32 s45, s45, 6
	s_mul_i32 s45, s45, 3
	s_lshr_b32 s45, 0x54e8f8, s45
	s_and_b32 s45, s45, 7
	s_lshl_b32 s45, s45, 5
	s_andn2_b32 s45, s45, 31
	v_add_u32_e32 v198, s45, v241
	v_ashrrev_i32_e32 v199, 31, v198
	v_lshl_add_u64 v[0:1], s[8:9], 0, v[198:199]
	v_mov_b64_e32 v[2:3], s[46:47]
	v_mad_u64_u32 v[2:3], s[46:47], v0, s93, v[2:3]
	v_mad_i32_i24 v3, v1, s93, v3
	v_lshl_add_u64 v[2:3], v[2:3], 0, v[164:165]
	global_load_dwordx4 v[96:99], v[2:3], off
	global_load_dwordx4 v[100:103], v[2:3], off offset:32
	global_load_dwordx4 v[104:107], v[2:3], off offset:64
	global_load_dwordx4 v[108:111], v[2:3], off offset:96
	v_mov_b64_e32 v[2:3], s[28:29]
	v_mad_u64_u32 v[2:3], s[46:47], v0, s93, v[2:3]
	v_mad_i32_i24 v3, v1, s93, v3
	v_lshl_add_u64 v[4:5], v[2:3], 0, v[164:165]
	global_load_dwordx4 v[0:3], v[4:5], off
	global_load_dwordx4 v[6:9], v[4:5], off offset:32
	s_add_i32 s44, s44, s42
	s_add_u32 s46, s28, s10
	s_addc_u32 s47, s29, s11
	v_mov_b32_e32 v32, 0
	v_mov_b32_e32 v33, v32
	v_mov_b32_e32 v46, v32
	v_mov_b32_e32 v47, v32
	v_mov_b32_e32 v34, v32
	v_mov_b32_e32 v35, v32
	v_mov_b32_e32 v36, v32
	v_mov_b32_e32 v37, v32
	v_mov_b32_e32 v38, v32
	v_mov_b32_e32 v39, v32
	v_mov_b32_e32 v40, v32
	v_mov_b32_e32 v41, v32
	v_mov_b32_e32 v42, v32
	v_mov_b32_e32 v43, v32
	v_mov_b32_e32 v44, v32
	v_mov_b32_e32 v45, v32
	v_mov_b64_e32 v[62:63], v[46:47]
	v_lshl_add_u64 v[200:201], v[160:161], 0, s[26:27]
	v_subrev_u32_e32 v243, s45, v242
	v_mov_b32_e32 v245, v157
	s_mov_b64 s[26:27], s[18:19]
	v_mov_b64_e32 v[60:61], v[44:45]
	v_mov_b64_e32 v[58:59], v[42:43]
	v_mov_b64_e32 v[56:57], v[40:41]
	v_mov_b64_e32 v[54:55], v[38:39]
	v_mov_b64_e32 v[52:53], v[36:37]
	v_mov_b64_e32 v[50:51], v[34:35]
	v_mov_b64_e32 v[48:49], v[32:33]
	v_mov_b32_e32 v244, v32
	s_waitcnt vmcnt(5)
	v_and_b32_e32 v14, 0xffff0000, v96
	s_waitcnt vmcnt(4)
	v_and_b32_e32 v15, 0xffff0000, v100
	v_lshlrev_b32_e32 v11, 16, v100
	v_lshlrev_b32_e32 v10, 16, v96
	s_waitcnt vmcnt(1)
	v_and_b32_e32 v16, 0xffff0000, v0
	s_waitcnt vmcnt(0)
	v_and_b32_e32 v17, 0xffff0000, v6
	v_lshlrev_b32_e32 v13, 16, v6
	v_lshlrev_b32_e32 v12, 16, v0
	v_pk_mul_f32 v[14:15], v[14:15], v[16:17]
	v_and_b32_e32 v6, 0xffff0000, v1
	v_pk_fma_f32 v[10:11], v[10:11], v[12:13], v[14:15]
	v_lshlrev_b32_e32 v13, 16, v101
	v_lshlrev_b32_e32 v12, 16, v97
	v_lshlrev_b32_e32 v15, 16, v7
	v_lshlrev_b32_e32 v14, 16, v1
	v_pk_fma_f32 v[10:11], v[12:13], v[14:15], v[10:11]
	v_and_b32_e32 v13, 0xffff0000, v101
	v_and_b32_e32 v12, 0xffff0000, v97
	v_and_b32_e32 v7, 0xffff0000, v7
	v_pk_fma_f32 v[0:1], v[12:13], v[6:7], v[10:11]
	v_lshlrev_b32_e32 v7, 16, v102
	v_lshlrev_b32_e32 v6, 16, v98
	v_lshlrev_b32_e32 v11, 16, v8
	v_lshlrev_b32_e32 v10, 16, v2
	v_pk_fma_f32 v[0:1], v[6:7], v[10:11], v[0:1]
	v_and_b32_e32 v7, 0xffff0000, v102
	v_and_b32_e32 v6, 0xffff0000, v98
	v_and_b32_e32 v11, 0xffff0000, v8
	v_and_b32_e32 v10, 0xffff0000, v2
	v_pk_fma_f32 v[0:1], v[6:7], v[10:11], v[0:1]
	v_lshlrev_b32_e32 v7, 16, v103
	v_lshlrev_b32_e32 v6, 16, v99
	v_lshlrev_b32_e32 v11, 16, v9
	v_lshlrev_b32_e32 v10, 16, v3
	v_pk_fma_f32 v[0:1], v[6:7], v[10:11], v[0:1]
	v_and_b32_e32 v7, 0xffff0000, v103
	v_and_b32_e32 v6, 0xffff0000, v99
	v_and_b32_e32 v9, 0xffff0000, v9
	v_and_b32_e32 v8, 0xffff0000, v3
	v_pk_fma_f32 v[0:1], v[6:7], v[8:9], v[0:1]
	v_and_b32_e32 v13, 0xffff0000, v108
	v_add_f32_e32 v0, 0, v0
	v_add_f32_e32 v16, v0, v1
	global_load_dwordx4 v[0:3], v[4:5], off offset:64
	s_nop 0
	global_load_dwordx4 v[4:7], v[4:5], off offset:96
	v_and_b32_e32 v12, 0xffff0000, v104
	v_lshlrev_b32_e32 v9, 16, v108
	v_lshlrev_b32_e32 v8, 16, v104
	s_waitcnt vmcnt(1)
	v_and_b32_e32 v14, 0xffff0000, v0
	s_waitcnt vmcnt(0)
	v_and_b32_e32 v15, 0xffff0000, v4
	v_lshlrev_b32_e32 v11, 16, v4
	v_lshlrev_b32_e32 v10, 16, v0
	v_pk_mul_f32 v[12:13], v[12:13], v[14:15]
	v_and_b32_e32 v4, 0xffff0000, v1
	v_pk_fma_f32 v[8:9], v[8:9], v[10:11], v[12:13]
	v_lshlrev_b32_e32 v11, 16, v109
	v_lshlrev_b32_e32 v10, 16, v105
	v_lshlrev_b32_e32 v13, 16, v5
	v_lshlrev_b32_e32 v12, 16, v1
	v_pk_fma_f32 v[8:9], v[10:11], v[12:13], v[8:9]
	v_and_b32_e32 v11, 0xffff0000, v109
	v_and_b32_e32 v10, 0xffff0000, v105
	v_and_b32_e32 v5, 0xffff0000, v5
	v_pk_fma_f32 v[0:1], v[10:11], v[4:5], v[8:9]
	v_lshlrev_b32_e32 v5, 16, v110
	v_lshlrev_b32_e32 v4, 16, v106
	v_lshlrev_b32_e32 v9, 16, v6
	v_lshlrev_b32_e32 v8, 16, v2
	v_pk_fma_f32 v[0:1], v[4:5], v[8:9], v[0:1]
	v_and_b32_e32 v5, 0xffff0000, v110
	v_and_b32_e32 v4, 0xffff0000, v106
	v_and_b32_e32 v9, 0xffff0000, v6
	v_and_b32_e32 v8, 0xffff0000, v2
	v_pk_fma_f32 v[0:1], v[4:5], v[8:9], v[0:1]
	v_lshlrev_b32_e32 v5, 16, v111
	v_lshlrev_b32_e32 v4, 16, v107
	v_lshlrev_b32_e32 v9, 16, v7
	v_lshlrev_b32_e32 v8, 16, v3
	v_pk_fma_f32 v[0:1], v[4:5], v[8:9], v[0:1]
	v_and_b32_e32 v5, 0xffff0000, v111
	v_and_b32_e32 v4, 0xffff0000, v107
	v_and_b32_e32 v7, 0xffff0000, v7
	v_and_b32_e32 v6, 0xffff0000, v3
	v_pk_fma_f32 v[0:1], v[4:5], v[6:7], v[0:1]
	s_nop 0
	v_add_f32_e32 v0, v16, v0
	v_add_f32_e32 v0, v0, v1
	v_mov_b32_e32 v1, v0
	s_nop 1
	v_permlane32_swap_b32_e32 v0, v1
	v_add_f32_e32 v199, v0, v1
	v_lshl_add_u64 v[0:1], s[46:47], 0, v[160:161]
	s_add_u32 s46, s28, s12
	s_addc_u32 s47, s29, s13
	v_lshl_add_u64 v[12:13], s[46:47], 0, v[160:161]
	global_load_dwordx4 v[0:3], v[0:1], off
	s_nop 0
	global_load_dwordx4 v[4:7], v[174:175], off
	global_load_dwordx4 v[8:11], v[176:177], off
	s_nop 0
	global_load_dwordx4 v[12:15], v[12:13], off
	s_nop 0
	global_load_dwordx4 v[16:19], v[178:179], off
	global_load_dwordx4 v[20:23], v[180:181], off
	s_add_u32 s46, s28, s14
	s_addc_u32 s47, s29, s15
	s_add_u32 s28, s28, s16
	s_addc_u32 s29, s29, s17
	s_add_i32 s45, s44, -1
	s_waitcnt vmcnt(5)
	ds_write_b128 v222, v[0:3]
	s_waitcnt vmcnt(4)
	ds_write_b128 v223, v[4:7] offset:9216
	s_waitcnt vmcnt(3)
	ds_write_b128 v223, v[8:11] offset:19456
	s_waitcnt vmcnt(2)
	ds_write_b128 v222, v[12:15] offset:29952
	s_waitcnt vmcnt(1)
	ds_write_b128 v223, v[16:19] offset:39168
	s_waitcnt vmcnt(0)
	ds_write_b128 v223, v[20:23] offset:49408
	v_lshl_add_u64 v[0:1], s[46:47], 0, v[160:161]
	global_load_dwordx4 v[112:115], v[0:1], off
	global_load_dwordx4 v[116:119], v[182:183], off
	global_load_dwordx4 v[120:123], v[184:185], off
	v_lshl_add_u64 v[0:1], s[28:29], 0, v[160:161]
	global_load_dwordx4 v[124:127], v[0:1], off
	global_load_dwordx4 v[128:131], v[186:187], off
	global_load_dwordx4 v[132:135], v[188:189], off
	s_waitcnt lgkmcnt(0)
	s_barrier
; template <int DQK, int DV, int MODE>
; __device__ __forceinline__ void attn_unit(LAS unsigned char* lds, const AttnP& P, size_t rowbase, int qb, const int tid, const int pm) {
;     ...
;     f32x16 o[NDB];
; #pragma unroll
;     for (int db = 0; db < NDB; ++db)
; #pragma unroll
;         for (int r = 0; r < 16; ++r) o[db][r] = 0.f;
;     float mref = sdiag, lrun = 0.f;
;     ...
;     for (int kt = 0; kt < NT; kt += 2) {
;         const int sb = (kt & 2);
;         const bool two_ = (kt + 1 <= ktlast);
;         if (kt <= ktlast && pm != 1) ATT_COMPUTE(kt, sb, true, (KPF2 && MODE == 0 && two_));
	v_mov_b64_e32 v[16:17], v[32:33]
	v_mov_b64_e32 v[0:1], v[32:33]
	v_mov_b64_e32 v[18:19], v[34:35]
	v_mov_b64_e32 v[20:21], v[36:37]
	v_mov_b64_e32 v[22:23], v[38:39]
	v_mov_b64_e32 v[24:25], v[40:41]
	v_mov_b64_e32 v[26:27], v[42:43]
	v_mov_b64_e32 v[28:29], v[44:45]
	v_mov_b64_e32 v[30:31], v[46:47]
	v_mov_b64_e32 v[2:3], v[34:35]
	v_mov_b64_e32 v[4:5], v[36:37]
	v_mov_b64_e32 v[6:7], v[38:39]
	v_mov_b64_e32 v[8:9], v[40:41]
	v_mov_b64_e32 v[10:11], v[42:43]
	v_mov_b64_e32 v[12:13], v[44:45]
	v_mov_b64_e32 v[14:15], v[46:47]
	s_mov_b32 s46, 0
	s_and_b32 s47, s46, 2
	s_cmp_gt_i32 s46, s44
	s_mul_i32 s28, s47, 0x7500
	s_cbranch_scc1 .LBB0_145

; template <int DQK, int DV, int MODE>
; __device__ __forceinline__ void attn_unit(LAS unsigned char* lds, const AttnP& P, size_t rowbase, int qb, const int tid, const int pm) {
;     ...
;     const int lane = tid & 63, wid = __builtin_amdgcn_readfirstlane(tid >> 6), r32 = lane & 31, hi = lane >> 5;
;     const int q0 = qb * 256, NT = 4 * qb + 4, ktlast = 4 * qb + (wid >> 1);
;     const int qpos = q0 + wid * 32 + r32;
;     bf16x8 qf[NKS];
;     {
;         const bf16_t* qrow = P.Q + (rowbase + qpos) * (size_t)P.ldq + hi * 8;
; #pragma unroll
;         for (int ks = 0; ks < NKS; ++ks) qf[ks] = *(const bf16x8*)(qrow + ks * 16);
;     }
;     float cq2 = 0.f;
;     if (MODE == 0) cq2 = P.bias[qpos];
;     float sdiag = 0.f;
;     {
;         const bf16_t* kd = P.K1 + (rowbase + qpos) * (size_t)P.ldk1 + hi * 8;
; #pragma unroll
;         for (int ks = 0; ks < NKS; ++ks) {
;             const u32x4 kv_ = (MODE == 1 && ks >= 4) ? *(const u32x4*)(P.K2 + (rowbase + qpos) * 32 + (ks - 4) * 16 + hi * 8) : *(const u32x4*)(kd + ks * 16);
;             const u32x4 qv_ = __builtin_bit_cast(u32x4, qf[ks]);
;             sdiag += bf_lo(qv_.x) * bf_lo(kv_.x) + bf_hi(qv_.x) * bf_hi(kv_.x) + bf_lo(qv_.y) * bf_lo(kv_.y) + bf_hi(qv_.y) * bf_hi(kv_.y)
; __device__ __forceinline__ void phase_attn_even(const Frame& F, const int pm) {
;     ...
;         const int stream = item >> 9, rem = item & 511, bh = rem >> 3, pr = rem & 7, b = bh >> 3, h = bh & 7;
;         const size_t rowbase = (size_t)b * SEQ;
;         AttnP P;
;         if (stream == 0) {
;             P.Q = proj + C_FQ + h * 64; P.ldq = EIN_NP; P.K1 = proj + C_FK + h * 64; P.ldk1 = EIN_NP; P.K2 = nullptr; P.V = proj + C_FV + h * 64; P.ldv = EIN_NP;
;             P.O = ao + h * 64; P.ldo = 1024; P.bias = ccum + (size_t)bh * SEQ; P.sl2 = 0.f; P.Oprev = nullptr; P.subln = nullptr; P.lam = 0.f; P.osc = 0.f;
;             attn_unit<64, 64, 0>(F.lds, P, rowbase, 15 - pr, F.tid, pm);
;             attn_unit<64, 64, 0>(F.lds, P, rowbase, pr, F.tid, pm);
;         } else {
;             P.Q = qmla + h * 96; P.ldq = 768; P.K1 = kvmla + h * 128; P.ldk1 = 1024; P.K2 = krope; P.V = kvmla + h * 128 + 64; P.ldv = 1024;
;             P.O = ao + 512 + h * 64; P.ldo = 1024; P.bias = nullptr; P.sl2 = 0.f; P.Oprev = nullptr; P.subln = nullptr; P.lam = 0.f; P.osc = 0.f;
;             attn_unit<96, 64, 1>(F.lds, P, rowbase, 15 - pr, F.tid, pm);
.LBB0_174:
	s_andn2_b64 vcc, exec, s[14:15]
	s_mov_b64 s[14:15], -1
	s_cbranch_vccnz .LBB0_166
	s_and_b32 s8, s83, 7
	v_writelane_b32 v254, s8, 59
	s_lshl_b32 s8, s83, 6
	s_bfe_u32 s97, s83, 0x30003
	s_and_b32 s94, s8, 0x7000
	s_cmpk_gt_u32 s83, 0x1ff
	v_lshlrev_b32_e32 v164, 1, v144
	s_cbranch_scc0 .LBB0_253
	s_mul_i32 s8, s97, 0xc0
	s_add_u32 s14, s4, s8
	s_addc_u32 s15, s5, 0
	s_lshl_b32 s8, s97, 8
	v_readlane_b32 s9, v254, 43
	s_add_u32 s16, s9, s8
	v_readlane_b32 s8, v254, 44
	s_addc_u32 s17, s8, 0
	v_readlane_b32 s8, v254, 59
	v_readfirstlane_b32 s9, v170
	s_xor_b32 s8, s8, 15
	s_lshr_b32 s13, s9, 6
	s_mul_i32 s13, s13, 3
	s_lshr_b32 s13, 0x54e8f8, s13
	s_and_b32 s13, s13, 7
	s_lshl_b32 s13, s13, 5
	s_lshl_b32 s12, s8, 8
	s_andn2_b32 s13, s13, 31
	s_add_i32 s13, s13, s12
	v_or_b32_e32 v140, s13, v145
	v_ashrrev_i32_e32 v141, 31, v140
	v_writelane_b32 v255, s14, 0
	v_lshl_add_u64 v[0:1], v[140:141], 0, s[94:95]
	s_waitcnt vmcnt(5)
	v_mov_b32_e32 v90, v165
	v_writelane_b32 v255, s15, 1
	v_mov_b64_e32 v[2:3], s[14:15]
	s_movk_i32 s14, 0x600
	v_mad_u64_u32 v[2:3], s[12:13], v0, s14, v[2:3]
	v_mad_i32_i24 v3, v1, s14, v3
	v_lshl_add_u64 v[2:3], v[2:3], 0, v[164:165]
	global_load_dwordx4 v[64:67], v[2:3], off
	global_load_dwordx4 v[68:71], v[2:3], off offset:32
	global_load_dwordx4 v[72:75], v[2:3], off offset:64
	global_load_dwordx4 v[76:79], v[2:3], off offset:96
	global_load_dwordx4 v[80:83], v[2:3], off offset:128
	global_load_dwordx4 v[84:87], v[2:3], off offset:160
	v_lshlrev_b64 v[2:3], 11, v[0:1]
	v_lshl_add_u64 v[2:3], s[16:17], 0, v[2:3]
	v_lshl_add_u64 v[2:3], v[2:3], 0, v[164:165]
	global_load_dwordx4 v[4:7], v[2:3], off
	v_lshlrev_b64 v[0:1], 6, v[0:1]
	s_lshl_b32 s12, s94, 11
	s_add_u32 s12, s16, s12
	v_writelane_b32 v255, s16, 2
	s_addc_u32 s13, s17, 0
	v_lshl_add_u64 v[132:133], v[146:147], 1, s[12:13]
	v_mov_b32_e32 v91, v165
	v_mov_b32_e32 v88, v165
	v_mov_b32_e32 v89, v165
	s_waitcnt vmcnt(11)
	v_mov_b64_e32 v[94:95], v[90:91]
	v_writelane_b32 v255, s17, 3
	v_mov_b64_e32 v[92:93], v[88:89]
	s_waitcnt vmcnt(6)
	v_and_b32_e32 v10, 0xffff0000, v64
	v_lshlrev_b32_e32 v8, 16, v64
	s_waitcnt vmcnt(5)
	v_and_b32_e32 v11, 0xffff0000, v68
	s_waitcnt vmcnt(0)
	v_lshlrev_b32_e32 v9, 16, v4
	v_and_b32_e32 v4, 0xffff0000, v4
	v_mul_f32_e32 v4, v10, v4
	v_fmac_f32_e32 v4, v8, v9
	v_lshlrev_b32_e32 v8, 16, v65
	v_lshlrev_b32_e32 v9, 16, v5
	v_fmac_f32_e32 v4, v8, v9
	v_and_b32_e32 v8, 0xffff0000, v65
	v_and_b32_e32 v5, 0xffff0000, v5
	v_fmac_f32_e32 v4, v8, v5
	v_lshlrev_b32_e32 v5, 16, v66
	v_lshlrev_b32_e32 v8, 16, v6
	v_fmac_f32_e32 v4, v5, v8
	v_and_b32_e32 v5, 0xffff0000, v66
	v_and_b32_e32 v6, 0xffff0000, v6
	v_fmac_f32_e32 v4, v5, v6
	v_lshlrev_b32_e32 v5, 16, v67
	v_lshlrev_b32_e32 v6, 16, v7
	v_fmac_f32_e32 v4, v5, v6
	v_and_b32_e32 v5, 0xffff0000, v67
	v_and_b32_e32 v6, 0xffff0000, v7
	v_fmac_f32_e32 v4, v5, v6
	v_add_f32_e32 v8, 0, v4
	global_load_dwordx4 v[4:7], v[2:3], off offset:32
	v_lshlrev_b32_e32 v9, 16, v68
	s_waitcnt vmcnt(0)
	v_lshlrev_b32_e32 v10, 16, v4
	v_and_b32_e32 v4, 0xffff0000, v4
	v_mul_f32_e32 v4, v11, v4
	v_fmac_f32_e32 v4, v9, v10
	v_lshlrev_b32_e32 v9, 16, v69
	v_lshlrev_b32_e32 v10, 16, v5
	v_fmac_f32_e32 v4, v9, v10
	v_and_b32_e32 v9, 0xffff0000, v69
	v_and_b32_e32 v5, 0xffff0000, v5
	v_fmac_f32_e32 v4, v9, v5
	v_lshlrev_b32_e32 v5, 16, v70
	v_lshlrev_b32_e32 v9, 16, v6
	v_fmac_f32_e32 v4, v5, v9
	v_and_b32_e32 v5, 0xffff0000, v70
	v_and_b32_e32 v6, 0xffff0000, v6
	v_fmac_f32_e32 v4, v5, v6
	v_lshlrev_b32_e32 v5, 16, v71
	v_lshlrev_b32_e32 v6, 16, v7
	v_fmac_f32_e32 v4, v5, v6
	v_and_b32_e32 v5, 0xffff0000, v71
	v_and_b32_e32 v6, 0xffff0000, v7
	v_fmac_f32_e32 v4, v5, v6
	v_add_f32_e32 v8, v8, v4
	global_load_dwordx4 v[4:7], v[2:3], off offset:64
	v_and_b32_e32 v11, 0xffff0000, v72
	v_lshlrev_b32_e32 v9, 16, v72
	s_waitcnt vmcnt(0)
; __device__ __forceinline__ float bf_lo(unsigned w) { return __uint_as_float(w << 16); }
; __device__ __forceinline__ float bf_hi(unsigned w) { return __uint_as_float(w & 0xffff0000u); }
; template <int DQK, int DV, int MODE>
; __device__ __forceinline__ void attn_unit(LAS unsigned char* lds, const AttnP& P, size_t rowbase, int qb, const int tid, const int pm) {
;     ...
;     {
;         const bf16_t* kd = P.K1 + (rowbase + qpos) * (size_t)P.ldk1 + hi * 8;
; #pragma unroll
;         for (int ks = 0; ks < NKS; ++ks) {
;             const u32x4 kv_ = (MODE == 1 && ks >= 4) ? *(const u32x4*)(P.K2 + (rowbase + qpos) * 32 + (ks - 4) * 16 + hi * 8) : *(const u32x4*)(kd + ks * 16);
;             const u32x4 qv_ = __builtin_bit_cast(u32x4, qf[ks]);
;             sdiag += bf_lo(qv_.x) * bf_lo(kv_.x) + bf_hi(qv_.x) * bf_hi(kv_.x) + bf_lo(qv_.y) * bf_lo(kv_.y) + bf_hi(qv_.y) * bf_hi(kv_.y)
;                    + bf_lo(qv_.z) * bf_lo(kv_.z) + bf_hi(qv_.z) * bf_hi(kv_.z) + bf_lo(qv_.w) * bf_lo(kv_.w) + bf_hi(qv_.w) * bf_hi(kv_.w);
;         }
;         auto rr_ = __builtin_amdgcn_permlane32_swap(__float_as_uint(sdiag), __float_as_uint(sdiag), false, false);
;         sdiag = __uint_as_float(rr_[0]) + __uint_as_float(rr_[1]);
	v_lshlrev_b32_e32 v10, 16, v4
	v_and_b32_e32 v4, 0xffff0000, v4
	v_mul_f32_e32 v4, v11, v4
	v_fmac_f32_e32 v4, v9, v10
	v_lshlrev_b32_e32 v9, 16, v73
	v_lshlrev_b32_e32 v10, 16, v5
	v_fmac_f32_e32 v4, v9, v10
	v_and_b32_e32 v9, 0xffff0000, v73
	v_and_b32_e32 v5, 0xffff0000, v5
	v_fmac_f32_e32 v4, v9, v5
	v_lshlrev_b32_e32 v5, 16, v74
	v_lshlrev_b32_e32 v9, 16, v6
	v_fmac_f32_e32 v4, v5, v9
	v_and_b32_e32 v5, 0xffff0000, v74
	v_and_b32_e32 v6, 0xffff0000, v6
	v_fmac_f32_e32 v4, v5, v6
	v_lshlrev_b32_e32 v5, 16, v75
	v_lshlrev_b32_e32 v6, 16, v7
	v_fmac_f32_e32 v4, v5, v6
	v_and_b32_e32 v5, 0xffff0000, v75
	v_and_b32_e32 v6, 0xffff0000, v7
	v_fmac_f32_e32 v4, v5, v6
	v_add_f32_e32 v6, v8, v4
	global_load_dwordx4 v[2:5], v[2:3], off offset:96
	v_and_b32_e32 v9, 0xffff0000, v76
	v_lshlrev_b32_e32 v7, 16, v76
	s_waitcnt vmcnt(0)
	v_lshlrev_b32_e32 v8, 16, v2
	v_and_b32_e32 v2, 0xffff0000, v2
	v_mul_f32_e32 v2, v9, v2
	v_fmac_f32_e32 v2, v7, v8
	v_lshlrev_b32_e32 v7, 16, v77
	v_lshlrev_b32_e32 v8, 16, v3
	v_fmac_f32_e32 v2, v7, v8
	v_and_b32_e32 v7, 0xffff0000, v77
	v_and_b32_e32 v3, 0xffff0000, v3
	v_fmac_f32_e32 v2, v7, v3
	v_lshlrev_b32_e32 v3, 16, v78
	v_lshlrev_b32_e32 v7, 16, v4
	v_fmac_f32_e32 v2, v3, v7
	v_and_b32_e32 v3, 0xffff0000, v78
	v_and_b32_e32 v4, 0xffff0000, v4
	v_fmac_f32_e32 v2, v3, v4
	v_lshlrev_b32_e32 v3, 16, v79
	v_lshlrev_b32_e32 v4, 16, v5
	v_fmac_f32_e32 v2, v3, v4
	v_and_b32_e32 v3, 0xffff0000, v79
	v_and_b32_e32 v4, 0xffff0000, v5
	v_fmac_f32_e32 v2, v3, v4
	v_lshl_add_u64 v[4:5], v[154:155], 0, v[0:1]
	v_add_f32_e32 v6, v6, v2
	global_load_dwordx4 v[0:3], v[4:5], off
	v_and_b32_e32 v9, 0xffff0000, v80
	v_lshlrev_b32_e32 v7, 16, v80
	s_waitcnt vmcnt(0)
	v_lshlrev_b32_e32 v8, 16, v0
	v_and_b32_e32 v0, 0xffff0000, v0
	v_mul_f32_e32 v0, v9, v0
	v_fmac_f32_e32 v0, v7, v8
	v_lshlrev_b32_e32 v7, 16, v81
	v_lshlrev_b32_e32 v8, 16, v1
	v_fmac_f32_e32 v0, v7, v8
	v_and_b32_e32 v7, 0xffff0000, v81
	v_and_b32_e32 v1, 0xffff0000, v1
	v_fmac_f32_e32 v0, v7, v1
	v_lshlrev_b32_e32 v1, 16, v82
	v_lshlrev_b32_e32 v7, 16, v2
	v_fmac_f32_e32 v0, v1, v7
	v_and_b32_e32 v1, 0xffff0000, v82
	v_and_b32_e32 v2, 0xffff0000, v2
	v_fmac_f32_e32 v0, v1, v2
	v_lshlrev_b32_e32 v1, 16, v83
	v_lshlrev_b32_e32 v2, 16, v3
	v_fmac_f32_e32 v0, v1, v2
	v_and_b32_e32 v1, 0xffff0000, v83
	v_and_b32_e32 v2, 0xffff0000, v3
	v_fmac_f32_e32 v0, v1, v2
	v_add_f32_e32 v6, v6, v0
	global_load_dwordx4 v[0:3], v[4:5], off offset:32
	v_and_b32_e32 v7, 0xffff0000, v84
	v_lshlrev_b32_e32 v4, 16, v84
	s_waitcnt vmcnt(0)
	v_lshlrev_b32_e32 v5, 16, v0
	v_and_b32_e32 v0, 0xffff0000, v0
	v_mul_f32_e32 v0, v7, v0
	v_fmac_f32_e32 v0, v4, v5
	v_lshlrev_b32_e32 v4, 16, v85
	v_lshlrev_b32_e32 v5, 16, v1
	v_fmac_f32_e32 v0, v4, v5
	v_and_b32_e32 v4, 0xffff0000, v85
	v_and_b32_e32 v1, 0xffff0000, v1
	v_fmac_f32_e32 v0, v4, v1
	v_lshlrev_b32_e32 v1, 16, v86
	v_lshlrev_b32_e32 v4, 16, v2
	v_fmac_f32_e32 v0, v1, v4
	v_and_b32_e32 v1, 0xffff0000, v86
	v_and_b32_e32 v2, 0xffff0000, v2
	v_fmac_f32_e32 v0, v1, v2
	v_lshlrev_b32_e32 v1, 16, v87
	v_lshlrev_b32_e32 v2, 16, v3
	v_fmac_f32_e32 v0, v1, v2
	v_and_b32_e32 v1, 0xffff0000, v87
	v_and_b32_e32 v2, 0xffff0000, v3
	v_fmac_f32_e32 v0, v1, v2
	v_add_f32_e32 v16, v6, v0
	global_load_dwordx4 v[0:3], v[132:133], off
	v_mov_b32_e32 v17, v16
	s_nop 1
	v_permlane32_swap_b32_e32 v16, v17
	s_and_saveexec_b64 s[14:15], s[6:7]
	s_cbranch_execz .LBB0_178
	s_lshl_b32 s12, s94, 6
	s_mov_b32 s13, s95
	v_lshl_add_u64 v[4:5], v[150:151], 0, s[12:13]
	global_load_dwordx4 v[92:95], v[4:5], off

; #define ATT_BAR() do { asm volatile("s_waitcnt lgkmcnt(0)" ::: "memory"); __builtin_amdgcn_s_barrier(); asm volatile("" ::: "memory"); } while (0)
; template <int DQK, int DV, int MODE>
; __device__ __forceinline__ void attn_unit(LAS unsigned char* lds, const AttnP& P, size_t rowbase, int qb, const int tid, const int pm) {
;     ...
;     ATT_LOAD(A, 0); ATT_LOAD(B, 1);
;     ATT_STORE(A, 0); ATT_STORE(B, 1);
;     ATT_LOAD(A, 2); ATT_LOAD(B, 3);
;     ATT_BAR();
;     for (int kt = 0; kt < NT; kt += 2) {
;         const int sb = (kt & 2);
;         const bool two_ = (kt + 1 <= ktlast);
;         if (kt <= ktlast && pm != 1) ATT_COMPUTE(kt, sb, true, (KPF2 && MODE == 0 && two_));
.LBB0_188:
	s_or_b64 exec, exec, s[14:15]
	global_load_dwordx4 v[108:111], v[138:139], off offset:128
	s_lshl_b32 s8, s8, 2
	s_lshr_b32 s12, s9, 6
	s_mul_i32 s12, s12, 3
	s_lshr_b32 s12, 0x54e8f8, s12
	s_and_b32 s12, s12, 7
	s_lshr_b32 s12, s12, 1
	s_add_i32 s12, s12, s8
	v_lshl_or_b32 v0, s12, 6, v218
	v_or_b32_e32 v1, 32, v0
	v_cmp_gt_i32_e64 s[16:17], v1, v140
	v_or_b32_e32 v1, 33, v0
	v_cmp_gt_i32_e64 s[20:21], v1, v140
	v_or_b32_e32 v1, 2, v0
	v_cmp_gt_i32_e64 s[22:23], v1, v140
	v_or_b32_e32 v1, 34, v0
	v_cmp_gt_i32_e64 s[24:25], v1, v140
	v_or_b32_e32 v1, 3, v0
	v_cmp_gt_i32_e64 s[26:27], v1, v140
	v_or_b32_e32 v1, 35, v0
	v_cmp_gt_i32_e64 s[28:29], v1, v140
	v_or_b32_e32 v1, 8, v0
	v_cmp_gt_i32_e64 s[30:31], v1, v140
	v_or_b32_e32 v1, 40, v0
	v_cmp_gt_i32_e64 s[34:35], v1, v140
	v_or_b32_e32 v1, 9, v0
	v_cmp_gt_i32_e64 s[36:37], v1, v140
	v_or_b32_e32 v1, 41, v0
	v_cmp_gt_i32_e64 s[38:39], v1, v140
	v_or_b32_e32 v1, 10, v0
	v_cmp_gt_i32_e64 s[40:41], v1, v140
	v_or_b32_e32 v1, 42, v0
	v_cmp_gt_i32_e64 s[42:43], v1, v140
	v_or_b32_e32 v1, 11, v0
	v_cmp_gt_i32_e64 s[44:45], v1, v140
	v_or_b32_e32 v1, 43, v0
	v_cmp_gt_i32_e64 s[46:47], v1, v140
	v_or_b32_e32 v1, 16, v0
	v_cmp_gt_i32_e64 s[48:49], v1, v140
	v_or_b32_e32 v1, 48, v0
	v_cmp_gt_i32_e64 s[50:51], v1, v140
	v_or_b32_e32 v1, 17, v0
	v_cmp_gt_i32_e64 s[52:53], v1, v140
	v_or_b32_e32 v1, 49, v0
	v_cmp_gt_i32_e64 s[54:55], v1, v140
	v_or_b32_e32 v1, 18, v0
	v_cmp_gt_i32_e64 s[56:57], v1, v140
	v_or_b32_e32 v1, 50, v0
	v_cmp_gt_i32_e64 s[58:59], v1, v140
	v_or_b32_e32 v1, 19, v0
	v_cmp_gt_i32_e64 s[60:61], v1, v140
	v_or_b32_e32 v1, 51, v0
	v_cmp_gt_i32_e64 s[62:63], v1, v140
	v_or_b32_e32 v1, 24, v0
	v_cmp_gt_i32_e64 s[64:65], v1, v140
	v_or_b32_e32 v1, 56, v0
	v_cmp_gt_i32_e64 s[66:67], v1, v140
	v_or_b32_e32 v1, 25, v0
	s_lshl_b32 s13, s83, 12
	v_cmp_gt_i32_e64 s[68:69], v1, v140
	v_or_b32_e32 v1, 57, v0
	s_and_b32 s84, s13, 0x1c0000
	s_lshl_b32 s13, s83, 17
	s_lshl_b32 s80, s83, 5
	v_cmp_gt_i32_e64 s[70:71], v1, v140
	v_or_b32_e32 v1, 26, v0
	s_mov_b32 s85, s95
	s_and_b32 s13, s13, 0x3800000
	s_and_b32 s80, s80, 0x700
	s_waitcnt lgkmcnt(0)
	s_barrier
	v_cmp_gt_i32_e64 s[72:73], v1, v140
	v_or_b32_e32 v1, 58, v0
	v_lshl_add_u64 v[128:129], v[148:149], 0, s[84:85]
	s_or_b32 s84, s80, s13
	v_cmp_gt_i32_e64 s[14:15], v0, v140
	v_cmp_lt_i32_e64 s[18:19], v0, v140
	v_cmp_gt_i32_e64 s[74:75], v1, v140
	v_or_b32_e32 v1, 27, v0
	v_or_b32_e32 v0, 59, v0
	v_lshl_add_u64 v[130:131], s[84:85], 0, v[156:157]
	s_add_i32 s9, s8, 4
	v_add_f32_e32 v141, v16, v17
	v_cmp_gt_i32_e64 s[76:77], v1, v140
	v_cmp_gt_i32_e64 s[78:79], v0, v140
	v_writelane_b32 v254, s83, 60
	s_add_i32 s13, s12, -1
	s_mov_b32 s83, 0
	v_mov_b32_e32 v16, v165
	v_mov_b32_e32 v17, v165
	v_mov_b32_e32 v18, v165
	v_mov_b32_e32 v19, v165
	v_mov_b32_e32 v20, v165
	v_mov_b32_e32 v21, v165
	v_mov_b32_e32 v22, v165
	v_mov_b32_e32 v23, v165
	v_mov_b32_e32 v24, v165
	v_mov_b32_e32 v25, v165
	v_mov_b32_e32 v26, v165
	v_mov_b32_e32 v27, v165
	v_mov_b32_e32 v28, v165
	v_mov_b32_e32 v29, v165
	v_mov_b32_e32 v30, v165
	v_mov_b32_e32 v31, v165
	v_mov_b32_e32 v0, v165
	v_mov_b32_e32 v1, v165
	v_mov_b32_e32 v2, v165
	v_mov_b32_e32 v3, v165
	v_mov_b32_e32 v4, v165
	v_mov_b32_e32 v5, v165
	v_mov_b32_e32 v6, v165
	v_mov_b32_e32 v7, v165
	v_mov_b32_e32 v8, v165
	v_mov_b32_e32 v9, v165
	v_mov_b32_e32 v10, v165
	v_mov_b32_e32 v11, v165
	v_mov_b32_e32 v12, v165
	v_mov_b32_e32 v13, v165
	v_mov_b32_e32 v14, v165
	v_mov_b32_e32 v15, v165
	v_mov_b32_e32 v174, 0
	v_mov_b64_e32 v[142:143], v[130:131]
	v_mov_b64_e32 v[162:163], v[128:129]
	s_and_b32 s84, s83, 2
	s_cmp_gt_i32 s83, s12
	s_mul_i32 s85, s84, 0x6500
	s_cbranch_scc1 .LBB0_194

; template <int DQK, int DV, int MODE>
; __device__ __forceinline__ void attn_unit(LAS unsigned char* lds, const AttnP& P, size_t rowbase, int qb, const int tid, const int pm) {
;     ...
;     float ltot; { auto rr_ = __builtin_amdgcn_permlane32_swap(__float_as_uint(lrun), __float_as_uint(lrun), false, false); ltot = __uint_as_float(rr_[0]) + __uint_as_float(rr_[1]); }
;     const float inv = 1.0f / ltot;
;     int qpe_ = qpos; asm volatile("" : "+v"(qpe_));
;     bf16_t* orow = P.O + (rowbase + qpe_) * (size_t)P.ldo + 8 * hi;
;     if (MODE == 2 && P.Oprev != nullptr) {
;         const bf16_t* prow = P.Oprev + (rowbase + qpe_) * (size_t)P.ldo + 8 * hi;
;         f32x4 cv[NDB][2][2]; float ss = 0.f;
; #pragma unroll
;         for (int db = 0; db < NDB; ++db)
; #pragma unroll
;             for (int a = 0; a < 4; a += 2) {
;                 const unsigned x0 = cvt_pk_bf16(o[db][4 * a] * inv, o[db][4 * a + 1] * inv), x1 = cvt_pk_bf16(o[db][4 * a + 2] * inv, o[db][4 * a + 3] * inv);
;                 const unsigned y0 = cvt_pk_bf16(o[db][4 * a + 4] * inv, o[db][4 * a + 5] * inv), y1 = cvt_pk_bf16(o[db][4 * a + 6] * inv, o[db][4 * a + 7] * inv);
;                 const auto s0_ = __builtin_amdgcn_permlane32_swap(x0, y0, false, false);
;                 const auto s1_ = __builtin_amdgcn_permlane32_swap(x1, y1, false, false);
;                 const u32x4 w1 = *(const u32x4*)(prow + db * 32 + a * 8);
;                 const f32x4 d0 = (f32x4){bf_lo(w1.x) - P.lam * bf_lo(s0_[0]), bf_hi(w1.x) - P.lam * bf_hi(s0_[0]), bf_lo(w1.y) - P.lam * bf_lo(s1_[0]), bf_hi(w1.y) - P.lam * bf_hi(s1_[0])};
;                 const f32x4 d1 = (f32x4){bf_lo(w1.z) - P.lam * bf_lo(s0_[1]), bf_hi(w1.z) - P.lam * bf_hi(s0_[1]), bf_lo(w1.w) - P.lam * bf_lo(s1_[1]), bf_hi(w1.w) - P.lam * bf_hi(s1_[1])};
;                 cv[db][a >> 1][0] = d0; cv[db][a >> 1][1] = d1;
;                 ss += (d0[0] * d0[0] + d0[1] * d0[1]) + (d0[2] * d0[2] + d0[3] * d0[3]) + (d1[0] * d1[0] + d1[1] * d1[1]) + (d1[2] * d1[2] + d1[3] * d1[3]);
;             }
;         { auto rr_ = __builtin_amdgcn_permlane32_swap(__float_as_uint(ss), __float_as_uint(ss), false, false); ss = __uint_as_float(rr_[0]) + __uint_as_float(rr_[1]); }
;         const float rs = rsqrtf(ss * (1.0f / 128.0f) + RMS_EPS) * P.osc;
;         const float* sgp = P.subln + 8 * hi;
; #pragma unroll
;         for (int db = 0; db < NDB; ++db)
.LBB0_214:
	v_mov_b32_e32 v32, v174
	v_readlane_b32 s97, v254, 62
	s_nop 0
	v_permlane32_swap_b32_e32 v174, v32
	s_lshl_b32 s8, s97, 7
	v_add_f32_e32 v32, v174, v32
	s_add_u32 s12, s88, s8
	v_div_scale_f32 v33, s[8:9], v32, v32, 1.0
	v_rcp_f32_e32 v34, v33
	s_waitcnt lgkmcnt(0)
	s_barrier
	v_fma_f32 v35, -v33, v34, 1.0
	v_fmac_f32_e32 v34, v35, v34
	v_div_scale_f32 v35, vcc, 1.0, v32, 1.0
	v_mul_f32_e32 v36, v35, v34
	v_fma_f32 v37, -v33, v36, v35
	v_fmac_f32_e32 v36, v37, v34
	v_fma_f32 v33, -v33, v36, v35
	v_div_fmas_f32 v33, v33, v34, v36
	v_div_fixup_f32 v34, v33, v32, 1.0
	v_mul_f32_e32 v16, v16, v34
	v_mul_f32_e32 v17, v17, v34
	v_cvt_pk_bf16_f32 v16, v16, v17
	v_mul_f32_e32 v17, v18, v34
	v_ashrrev_i32_e32 v141, 31, v140
	v_mul_f32_e32 v18, v19, v34
	v_lshl_add_u64 v[32:33], v[140:141], 0, s[94:95]
	v_cvt_pk_bf16_f32 v17, v17, v18
	v_mul_f32_e32 v18, v20, v34
	v_mul_f32_e32 v19, v21, v34
	s_addc_u32 s13, s89, 0
	v_lshlrev_b64 v[32:33], 11, v[32:33]
	v_cvt_pk_bf16_f32 v18, v18, v19
	v_mul_f32_e32 v19, v22, v34
	v_writelane_b32 v255, s12, 7
	v_mul_f32_e32 v20, v23, v34
	v_cvt_pk_bf16_f32 v19, v19, v20
	v_permlane32_swap_b32_e32 v16, v18
	v_lshl_add_u64 v[32:33], s[12:13], 0, v[32:33]
	v_lshl_add_u64 v[32:33], v[32:33], 0, v[164:165]
	v_permlane32_swap_b32_e32 v17, v19
	global_store_dwordx4 v[32:33], v[16:19], off offset:1024
	v_mul_f32_e32 v20, v31, v34
	v_mul_f32_e32 v0, v0, v34
	v_mul_f32_e32 v16, v24, v34
	v_mul_f32_e32 v17, v25, v34
	v_cvt_pk_bf16_f32 v16, v16, v17
	v_mul_f32_e32 v17, v26, v34
	v_mul_f32_e32 v18, v27, v34
	v_cvt_pk_bf16_f32 v17, v17, v18
	v_mul_f32_e32 v18, v28, v34
	v_mul_f32_e32 v19, v29, v34
	v_cvt_pk_bf16_f32 v18, v18, v19
	v_mul_f32_e32 v19, v30, v34
	v_cvt_pk_bf16_f32 v19, v19, v20
	v_permlane32_swap_b32_e32 v16, v18
	s_nop 0
	v_permlane32_swap_b32_e32 v17, v19
	v_mul_f32_e32 v1, v1, v34
	global_store_dwordx4 v[32:33], v[16:19], off offset:1056
	v_cvt_pk_bf16_f32 v0, v0, v1
	v_mul_f32_e32 v1, v2, v34
	v_mul_f32_e32 v2, v3, v34
	v_cvt_pk_bf16_f32 v1, v1, v2
	v_mul_f32_e32 v2, v4, v34
	v_mul_f32_e32 v3, v5, v34
	v_cvt_pk_bf16_f32 v2, v2, v3
	v_mul_f32_e32 v3, v6, v34
	v_mul_f32_e32 v4, v7, v34
	v_cvt_pk_bf16_f32 v3, v3, v4
	v_permlane32_swap_b32_e32 v0, v2
	v_permlane32_swap_b32_e32 v1, v3
	global_store_dwordx4 v[32:33], v[0:3], off offset:1088
	v_readfirstlane_b32 s9, v170
	v_writelane_b32 v255, s13, 8
	v_mul_f32_e32 v0, v8, v34
	v_mul_f32_e32 v1, v9, v34
	v_cvt_pk_bf16_f32 v0, v0, v1
	v_mul_f32_e32 v1, v10, v34
	v_mul_f32_e32 v2, v11, v34
	v_readlane_b32 s8, v254, 59
	s_lshr_b32 s12, s9, 6
	s_mul_i32 s12, s12, 3
	s_lshr_b32 s12, 0x54e8f8, s12
	s_and_b32 s12, s12, 7
	s_lshl_b32 s12, s12, 5
	v_cvt_pk_bf16_f32 v1, v1, v2
	v_mul_f32_e32 v2, v12, v34
	v_mul_f32_e32 v3, v13, v34
	s_lshl_b32 s8, s8, 8
	s_andn2_b32 s12, s12, 31
	v_cvt_pk_bf16_f32 v2, v2, v3
	v_mul_f32_e32 v3, v14, v34
	s_add_i32 s12, s12, s8
	v_mul_f32_e32 v4, v15, v34
	v_cvt_pk_bf16_f32 v3, v3, v4
	v_or_b32_e32 v140, s12, v145
	v_readlane_b32 s12, v255, 0
	v_permlane32_swap_b32_e32 v0, v2
	v_permlane32_swap_b32_e32 v1, v3
	v_ashrrev_i32_e32 v141, 31, v140
	v_readlane_b32 s13, v255, 1
	global_store_dwordx4 v[32:33], v[0:3], off offset:1120
	s_movk_i32 s8, 0x600
	s_waitcnt vmcnt(5)
	v_mov_b32_e32 v90, v165
	v_lshl_add_u64 v[0:1], v[140:141], 0, s[94:95]
	v_mov_b64_e32 v[2:3], s[12:13]
	v_mad_u64_u32 v[2:3], s[12:13], v0, s8, v[2:3]
	v_mad_i32_i24 v3, v1, s8, v3
	v_lshl_add_u64 v[2:3], v[2:3], 0, v[164:165]
	v_readlane_b32 s12, v255, 2
	global_load_dwordx4 v[64:67], v[2:3], off
	global_load_dwordx4 v[68:71], v[2:3], off offset:32
	global_load_dwordx4 v[72:75], v[2:3], off offset:64
	global_load_dwordx4 v[76:79], v[2:3], off offset:96
	global_load_dwordx4 v[80:83], v[2:3], off offset:128
	global_load_dwordx4 v[84:87], v[2:3], off offset:160
	v_lshlrev_b64 v[2:3], 11, v[0:1]
	v_readlane_b32 s13, v255, 3
	v_lshlrev_b64 v[0:1], 6, v[0:1]
	v_mov_b32_e32 v91, v165
	v_lshl_add_u64 v[2:3], s[12:13], 0, v[2:3]
	v_lshl_add_u64 v[2:3], v[2:3], 0, v[164:165]
	global_load_dwordx4 v[4:7], v[2:3], off
	v_mov_b32_e32 v88, v165
	v_mov_b32_e32 v89, v165
	v_mov_b64_e32 v[94:95], v[90:91]
	v_mov_b64_e32 v[92:93], v[88:89]
	s_waitcnt vmcnt(6)
	v_and_b32_e32 v10, 0xffff0000, v64
	v_lshlrev_b32_e32 v8, 16, v64
	s_waitcnt vmcnt(5)
	v_and_b32_e32 v11, 0xffff0000, v68
	s_waitcnt vmcnt(0)
	v_lshlrev_b32_e32 v9, 16, v4
	v_and_b32_e32 v4, 0xffff0000, v4
	v_mul_f32_e32 v4, v10, v4
	v_fmac_f32_e32 v4, v8, v9
	v_lshlrev_b32_e32 v8, 16, v65
	v_lshlrev_b32_e32 v9, 16, v5
	v_fmac_f32_e32 v4, v8, v9
	v_and_b32_e32 v8, 0xffff0000, v65
	v_and_b32_e32 v5, 0xffff0000, v5
	v_fmac_f32_e32 v4, v8, v5
	v_lshlrev_b32_e32 v5, 16, v66
	v_lshlrev_b32_e32 v8, 16, v6
	v_fmac_f32_e32 v4, v5, v8
	v_and_b32_e32 v5, 0xffff0000, v66
	v_and_b32_e32 v6, 0xffff0000, v6
	v_fmac_f32_e32 v4, v5, v6
	v_lshlrev_b32_e32 v5, 16, v67
	v_lshlrev_b32_e32 v6, 16, v7
	v_fmac_f32_e32 v4, v5, v6
	v_and_b32_e32 v5, 0xffff0000, v67
	v_and_b32_e32 v6, 0xffff0000, v7
	v_fmac_f32_e32 v4, v5, v6
	v_add_f32_e32 v8, 0, v4
	global_load_dwordx4 v[4:7], v[2:3], off offset:32
	v_lshlrev_b32_e32 v9, 16, v68
	s_waitcnt vmcnt(0)
; __device__ __forceinline__ float bf_lo(unsigned w) { return __uint_as_float(w << 16); }
; __device__ __forceinline__ float bf_hi(unsigned w) { return __uint_as_float(w & 0xffff0000u); }
; template <int DQK, int DV, int MODE>
; __device__ __forceinline__ void attn_unit(LAS unsigned char* lds, const AttnP& P, size_t rowbase, int qb, const int tid, const int pm) {
;     ...
;     {
;         const bf16_t* kd = P.K1 + (rowbase + qpos) * (size_t)P.ldk1 + hi * 8;
; #pragma unroll
;         for (int ks = 0; ks < NKS; ++ks) {
;             const u32x4 kv_ = (MODE == 1 && ks >= 4) ? *(const u32x4*)(P.K2 + (rowbase + qpos) * 32 + (ks - 4) * 16 + hi * 8) : *(const u32x4*)(kd + ks * 16);
;             const u32x4 qv_ = __builtin_bit_cast(u32x4, qf[ks]);
;             sdiag += bf_lo(qv_.x) * bf_lo(kv_.x) + bf_hi(qv_.x) * bf_hi(kv_.x) + bf_lo(qv_.y) * bf_lo(kv_.y) + bf_hi(qv_.y) * bf_hi(kv_.y)
;                    + bf_lo(qv_.z) * bf_lo(kv_.z) + bf_hi(qv_.z) * bf_hi(kv_.z) + bf_lo(qv_.w) * bf_lo(kv_.w) + bf_hi(qv_.w) * bf_hi(kv_.w);
;         }
;         auto rr_ = __builtin_amdgcn_permlane32_swap(__float_as_uint(sdiag), __float_as_uint(sdiag), false, false);
;         sdiag = __uint_as_float(rr_[0]) + __uint_as_float(rr_[1]);
	v_lshlrev_b32_e32 v10, 16, v4
	v_and_b32_e32 v4, 0xffff0000, v4
	v_mul_f32_e32 v4, v11, v4
	v_fmac_f32_e32 v4, v9, v10
	v_lshlrev_b32_e32 v9, 16, v69
	v_lshlrev_b32_e32 v10, 16, v5
	v_fmac_f32_e32 v4, v9, v10
	v_and_b32_e32 v9, 0xffff0000, v69
	v_and_b32_e32 v5, 0xffff0000, v5
	v_fmac_f32_e32 v4, v9, v5
	v_lshlrev_b32_e32 v5, 16, v70
	v_lshlrev_b32_e32 v9, 16, v6
	v_fmac_f32_e32 v4, v5, v9
	v_and_b32_e32 v5, 0xffff0000, v70
	v_and_b32_e32 v6, 0xffff0000, v6
	v_fmac_f32_e32 v4, v5, v6
	v_lshlrev_b32_e32 v5, 16, v71
	v_lshlrev_b32_e32 v6, 16, v7
	v_fmac_f32_e32 v4, v5, v6
	v_and_b32_e32 v5, 0xffff0000, v71
	v_and_b32_e32 v6, 0xffff0000, v7
	v_fmac_f32_e32 v4, v5, v6
	v_add_f32_e32 v8, v8, v4
	global_load_dwordx4 v[4:7], v[2:3], off offset:64
	v_and_b32_e32 v11, 0xffff0000, v72
	v_lshlrev_b32_e32 v9, 16, v72
	s_waitcnt vmcnt(0)
	v_lshlrev_b32_e32 v10, 16, v4
	v_and_b32_e32 v4, 0xffff0000, v4
	v_mul_f32_e32 v4, v11, v4
	v_fmac_f32_e32 v4, v9, v10
	v_lshlrev_b32_e32 v9, 16, v73
	v_lshlrev_b32_e32 v10, 16, v5
	v_fmac_f32_e32 v4, v9, v10
	v_and_b32_e32 v9, 0xffff0000, v73
	v_and_b32_e32 v5, 0xffff0000, v5
	v_fmac_f32_e32 v4, v9, v5
	v_lshlrev_b32_e32 v5, 16, v74
	v_lshlrev_b32_e32 v9, 16, v6
	v_fmac_f32_e32 v4, v5, v9
	v_and_b32_e32 v5, 0xffff0000, v74
	v_and_b32_e32 v6, 0xffff0000, v6
	v_fmac_f32_e32 v4, v5, v6
	v_lshlrev_b32_e32 v5, 16, v75
	v_lshlrev_b32_e32 v6, 16, v7
	v_fmac_f32_e32 v4, v5, v6
	v_and_b32_e32 v5, 0xffff0000, v75
	v_and_b32_e32 v6, 0xffff0000, v7
	v_fmac_f32_e32 v4, v5, v6
	v_add_f32_e32 v6, v8, v4
	global_load_dwordx4 v[2:5], v[2:3], off offset:96
	v_and_b32_e32 v9, 0xffff0000, v76
	v_lshlrev_b32_e32 v7, 16, v76
	s_waitcnt vmcnt(0)
	v_lshlrev_b32_e32 v8, 16, v2
	v_and_b32_e32 v2, 0xffff0000, v2
	v_mul_f32_e32 v2, v9, v2
	v_fmac_f32_e32 v2, v7, v8
	v_lshlrev_b32_e32 v7, 16, v77
	v_lshlrev_b32_e32 v8, 16, v3
	v_fmac_f32_e32 v2, v7, v8
	v_and_b32_e32 v7, 0xffff0000, v77
	v_and_b32_e32 v3, 0xffff0000, v3
	v_fmac_f32_e32 v2, v7, v3
	v_lshlrev_b32_e32 v3, 16, v78
	v_lshlrev_b32_e32 v7, 16, v4
	v_fmac_f32_e32 v2, v3, v7
	v_and_b32_e32 v3, 0xffff0000, v78
	v_and_b32_e32 v4, 0xffff0000, v4
	v_fmac_f32_e32 v2, v3, v4
	v_lshlrev_b32_e32 v3, 16, v79
	v_lshlrev_b32_e32 v4, 16, v5
	v_fmac_f32_e32 v2, v3, v4
	v_and_b32_e32 v3, 0xffff0000, v79
	v_and_b32_e32 v4, 0xffff0000, v5
	v_fmac_f32_e32 v2, v3, v4
	v_lshl_add_u64 v[4:5], v[154:155], 0, v[0:1]
	v_add_f32_e32 v6, v6, v2
	global_load_dwordx4 v[0:3], v[4:5], off
	v_and_b32_e32 v9, 0xffff0000, v80
	v_lshlrev_b32_e32 v7, 16, v80
	s_waitcnt vmcnt(0)
	v_lshlrev_b32_e32 v8, 16, v0
	v_and_b32_e32 v0, 0xffff0000, v0
	v_mul_f32_e32 v0, v9, v0
	v_fmac_f32_e32 v0, v7, v8
	v_lshlrev_b32_e32 v7, 16, v81
	v_lshlrev_b32_e32 v8, 16, v1
	v_fmac_f32_e32 v0, v7, v8
	v_and_b32_e32 v7, 0xffff0000, v81
	v_and_b32_e32 v1, 0xffff0000, v1
	v_fmac_f32_e32 v0, v7, v1
	v_lshlrev_b32_e32 v1, 16, v82
	v_lshlrev_b32_e32 v7, 16, v2
	v_fmac_f32_e32 v0, v1, v7
	v_and_b32_e32 v1, 0xffff0000, v82
	v_and_b32_e32 v2, 0xffff0000, v2
	v_fmac_f32_e32 v0, v1, v2
	v_lshlrev_b32_e32 v1, 16, v83
	v_lshlrev_b32_e32 v2, 16, v3
	v_fmac_f32_e32 v0, v1, v2
	v_and_b32_e32 v1, 0xffff0000, v83
	v_and_b32_e32 v2, 0xffff0000, v3
	v_fmac_f32_e32 v0, v1, v2
	v_add_f32_e32 v6, v6, v0
	global_load_dwordx4 v[0:3], v[4:5], off offset:32
	v_and_b32_e32 v7, 0xffff0000, v84
	v_lshlrev_b32_e32 v4, 16, v84
	s_waitcnt vmcnt(0)
	v_lshlrev_b32_e32 v5, 16, v0
	v_and_b32_e32 v0, 0xffff0000, v0
	v_mul_f32_e32 v0, v7, v0
	v_fmac_f32_e32 v0, v4, v5
	v_lshlrev_b32_e32 v4, 16, v85
	v_lshlrev_b32_e32 v5, 16, v1
	v_fmac_f32_e32 v0, v4, v5
	v_and_b32_e32 v4, 0xffff0000, v85
	v_and_b32_e32 v1, 0xffff0000, v1
	v_fmac_f32_e32 v0, v4, v1
	v_lshlrev_b32_e32 v1, 16, v86
	v_lshlrev_b32_e32 v4, 16, v2
	v_fmac_f32_e32 v0, v1, v4
	v_and_b32_e32 v1, 0xffff0000, v86
	v_and_b32_e32 v2, 0xffff0000, v2
	v_fmac_f32_e32 v0, v1, v2
	v_lshlrev_b32_e32 v1, 16, v87
	v_lshlrev_b32_e32 v2, 16, v3
	v_fmac_f32_e32 v0, v1, v2
	v_and_b32_e32 v1, 0xffff0000, v87
	v_and_b32_e32 v2, 0xffff0000, v3
	v_fmac_f32_e32 v0, v1, v2
	v_add_f32_e32 v16, v6, v0
	global_load_dwordx4 v[0:3], v[132:133], off
	v_mov_b32_e32 v17, v16
	s_nop 1
	v_permlane32_swap_b32_e32 v16, v17
	s_and_saveexec_b64 s[14:15], s[6:7]
	s_cbranch_execz .LBB0_216
	s_lshl_b32 s12, s94, 6
	s_mov_b32 s13, s95
	v_lshl_add_u64 v[4:5], v[150:151], 0, s[12:13]
	global_load_dwordx4 v[92:95], v[4:5], off

; #define ATT_BAR() do { asm volatile("s_waitcnt lgkmcnt(0)" ::: "memory"); __builtin_amdgcn_s_barrier(); asm volatile("" ::: "memory"); } while (0)
; template <int DQK, int DV, int MODE>
; __device__ __forceinline__ void attn_unit(LAS unsigned char* lds, const AttnP& P, size_t rowbase, int qb, const int tid, const int pm) {
;     ...
;     ATT_LOAD(A, 0); ATT_LOAD(B, 1);
;     ATT_STORE(A, 0); ATT_STORE(B, 1);
;     ATT_LOAD(A, 2); ATT_LOAD(B, 3);
;     ATT_BAR();
;     for (int kt = 0; kt < NT; kt += 2) {
;         const int sb = (kt & 2);
;         const bool two_ = (kt + 1 <= ktlast);
;         if (kt <= ktlast && pm != 1) ATT_COMPUTE(kt, sb, true, (KPF2 && MODE == 0 && two_));
.LBB0_226:
	s_or_b64 exec, exec, s[14:15]
	global_load_dwordx4 v[108:111], v[138:139], off offset:128
	v_readlane_b32 s8, v254, 59
	s_lshl_b32 s8, s8, 2
	s_lshr_b32 s12, s9, 6
	s_mul_i32 s12, s12, 3
	s_lshr_b32 s12, 0x54e8f8, s12
	s_and_b32 s12, s12, 7
	s_lshr_b32 s12, s12, 1
	s_add_i32 s12, s12, s8
	v_lshl_or_b32 v0, s12, 6, v218
	v_or_b32_e32 v1, 32, v0
	v_cmp_gt_i32_e64 s[16:17], v1, v140
	v_or_b32_e32 v1, 33, v0
	v_cmp_gt_i32_e64 s[20:21], v1, v140
	v_or_b32_e32 v1, 2, v0
	v_cmp_gt_i32_e64 s[22:23], v1, v140
	v_or_b32_e32 v1, 34, v0
	v_cmp_gt_i32_e64 s[24:25], v1, v140
	v_or_b32_e32 v1, 3, v0
	v_cmp_gt_i32_e64 s[26:27], v1, v140
	v_or_b32_e32 v1, 35, v0
	v_cmp_gt_i32_e64 s[28:29], v1, v140
	v_or_b32_e32 v1, 8, v0
	v_cmp_gt_i32_e64 s[30:31], v1, v140
	v_or_b32_e32 v1, 40, v0
	v_cmp_gt_i32_e64 s[34:35], v1, v140
	v_or_b32_e32 v1, 9, v0
	v_cmp_gt_i32_e64 s[36:37], v1, v140
	v_or_b32_e32 v1, 41, v0
	v_cmp_gt_i32_e64 s[38:39], v1, v140
	v_or_b32_e32 v1, 10, v0
	v_cmp_gt_i32_e64 s[40:41], v1, v140
	v_or_b32_e32 v1, 42, v0
	v_cmp_gt_i32_e64 s[42:43], v1, v140
	v_or_b32_e32 v1, 11, v0
	v_cmp_gt_i32_e64 s[44:45], v1, v140
	v_or_b32_e32 v1, 43, v0
	v_cmp_gt_i32_e64 s[46:47], v1, v140
	v_or_b32_e32 v1, 16, v0
	v_cmp_gt_i32_e64 s[48:49], v1, v140
	v_or_b32_e32 v1, 48, v0
	v_cmp_gt_i32_e64 s[50:51], v1, v140
	v_or_b32_e32 v1, 17, v0
	v_cmp_gt_i32_e64 s[52:53], v1, v140
	v_or_b32_e32 v1, 49, v0
	v_cmp_gt_i32_e64 s[54:55], v1, v140
	v_or_b32_e32 v1, 18, v0
	v_cmp_gt_i32_e64 s[56:57], v1, v140
	v_or_b32_e32 v1, 50, v0
	v_cmp_gt_i32_e64 s[58:59], v1, v140
	v_or_b32_e32 v1, 19, v0
	v_cmp_gt_i32_e64 s[60:61], v1, v140
	v_or_b32_e32 v1, 51, v0
	v_cmp_gt_i32_e64 s[62:63], v1, v140
	v_or_b32_e32 v1, 24, v0
	v_cmp_gt_i32_e64 s[64:65], v1, v140
	v_or_b32_e32 v1, 56, v0
	v_cmp_gt_i32_e64 s[66:67], v1, v140
	v_or_b32_e32 v1, 25, v0
	v_cmp_gt_i32_e64 s[68:69], v1, v140
	v_or_b32_e32 v1, 57, v0
	v_cmp_gt_i32_e64 s[70:71], v1, v140
	v_or_b32_e32 v1, 26, v0
	s_waitcnt lgkmcnt(0)
	s_barrier
	v_cmp_gt_i32_e64 s[72:73], v1, v140
	v_or_b32_e32 v1, 58, v0
	v_cmp_gt_i32_e64 s[14:15], v0, v140
	v_cmp_lt_i32_e64 s[18:19], v0, v140
	v_cmp_gt_i32_e64 s[74:75], v1, v140
	v_or_b32_e32 v1, 27, v0
	v_or_b32_e32 v0, 59, v0
	s_add_i32 s9, s8, 4
	v_add_f32_e32 v132, v16, v17
	v_cmp_gt_i32_e64 s[76:77], v1, v140
	v_cmp_gt_i32_e64 s[78:79], v0, v140
	s_add_i32 s13, s12, -1
	s_mov_b32 s86, 0
	v_mov_b32_e32 v16, v165
	v_mov_b32_e32 v17, v165
	v_mov_b32_e32 v18, v165
	v_mov_b32_e32 v19, v165
	v_mov_b32_e32 v20, v165
	v_mov_b32_e32 v21, v165
	v_mov_b32_e32 v22, v165
	v_mov_b32_e32 v23, v165
	v_mov_b32_e32 v24, v165
	v_mov_b32_e32 v25, v165
	v_mov_b32_e32 v26, v165
	v_mov_b32_e32 v27, v165
	v_mov_b32_e32 v28, v165
	v_mov_b32_e32 v29, v165
	v_mov_b32_e32 v30, v165
	v_mov_b32_e32 v31, v165
	v_mov_b32_e32 v0, v165
	v_mov_b32_e32 v1, v165
	v_mov_b32_e32 v2, v165
	v_mov_b32_e32 v3, v165
	v_mov_b32_e32 v4, v165
	v_mov_b32_e32 v5, v165
	v_mov_b32_e32 v6, v165
	v_mov_b32_e32 v7, v165
	v_mov_b32_e32 v8, v165
	v_mov_b32_e32 v9, v165
	v_mov_b32_e32 v10, v165
	v_mov_b32_e32 v11, v165
	v_mov_b32_e32 v12, v165
	v_mov_b32_e32 v13, v165
	v_mov_b32_e32 v14, v165
	v_mov_b32_e32 v15, v165
	v_mov_b32_e32 v133, 0
	s_and_b32 s84, s86, 2
	s_cmp_gt_i32 s86, s12
	s_mul_i32 s80, s84, 0x6500
	s_cbranch_scc1 .LBB0_232

; __device__ __forceinline__ float bf_lo(unsigned w) { return __uint_as_float(w << 16); }
; __device__ __forceinline__ float bf_hi(unsigned w) { return __uint_as_float(w & 0xffff0000u); }
; template <int DQK, int DV, int MODE>
; __device__ __forceinline__ void attn_unit(LAS unsigned char* lds, const AttnP& P, size_t rowbase, int qb, const int tid, const int pm) {
;     ...
;     const int lane = tid & 63, wid = __builtin_amdgcn_readfirstlane(tid >> 6), r32 = lane & 31, hi = lane >> 5;
;     const int q0 = qb * 256, NT = 4 * qb + 4, ktlast = 4 * qb + (wid >> 1);
;     const int qpos = q0 + wid * 32 + r32;
;     bf16x8 qf[NKS];
;     {
;         const bf16_t* qrow = P.Q + (rowbase + qpos) * (size_t)P.ldq + hi * 8;
; #pragma unroll
;         for (int ks = 0; ks < NKS; ++ks) qf[ks] = *(const bf16x8*)(qrow + ks * 16);
;     }
;     float cq2 = 0.f;
;     if (MODE == 0) cq2 = P.bias[qpos];
;     float sdiag = 0.f;
;     {
;         const bf16_t* kd = P.K1 + (rowbase + qpos) * (size_t)P.ldk1 + hi * 8;
; #pragma unroll
;         for (int ks = 0; ks < NKS; ++ks) {
;             const u32x4 kv_ = (MODE == 1 && ks >= 4) ? *(const u32x4*)(P.K2 + (rowbase + qpos) * 32 + (ks - 4) * 16 + hi * 8) : *(const u32x4*)(kd + ks * 16);
;             const u32x4 qv_ = __builtin_bit_cast(u32x4, qf[ks]);
;             sdiag += bf_lo(qv_.x) * bf_lo(kv_.x) + bf_hi(qv_.x) * bf_hi(kv_.x) + bf_lo(qv_.y) * bf_lo(kv_.y) + bf_hi(qv_.y) * bf_hi(kv_.y)
;                    + bf_lo(qv_.z) * bf_lo(kv_.z) + bf_hi(qv_.z) * bf_hi(kv_.z) + bf_lo(qv_.w) * bf_lo(kv_.w) + bf_hi(qv_.w) * bf_hi(kv_.w);
;         }
;         auto rr_ = __builtin_amdgcn_permlane32_swap(__float_as_uint(sdiag), __float_as_uint(sdiag), false, false);
;         sdiag = __uint_as_float(rr_[0]) + __uint_as_float(rr_[1]);
; __device__ __forceinline__ void phase_attn_even(const Frame& F, const int pm) {
;     ...
;         if (stream == 0) {
;             P.Q = proj + C_FQ + h * 64; P.ldq = EIN_NP; P.K1 = proj + C_FK + h * 64; P.ldk1 = EIN_NP; P.K2 = nullptr; P.V = proj + C_FV + h * 64; P.ldv = EIN_NP;
;             P.O = ao + h * 64; P.ldo = 1024; P.bias = ccum + (size_t)bh * SEQ; P.sl2 = 0.f; P.Oprev = nullptr; P.subln = nullptr; P.lam = 0.f; P.osc = 0.f;
;             attn_unit<64, 64, 0>(F.lds, P, rowbase, 15 - pr, F.tid, pm);
.LBB0_253:
	s_and_b64 vcc, exec, s[14:15]
	s_cbranch_vccz .LBB0_165
	s_lshr_b32 s8, s83, 3
	s_lshl_b32 s9, s97, 7
	s_add_u32 s16, s0, s9
	s_addc_u32 s17, s1, 0
	v_readlane_b32 s12, v254, 47
	s_add_u32 s20, s12, s9
	v_readlane_b32 s12, v254, 48
	s_addc_u32 s21, s12, 0
	v_readlane_b32 s12, v254, 49
	s_add_u32 s12, s12, s9
	v_readlane_b32 s9, v254, 50
	s_addc_u32 s13, s9, 0
	s_lshl_b32 s80, s8, 12
	s_mov_b32 s81, s95
	s_lshl_b64 s[8:9], s[80:81], 2
	v_readlane_b32 s14, v254, 45
	s_add_u32 s22, s14, s8
	v_readlane_b32 s8, v254, 46
	s_addc_u32 s23, s8, s9
	v_readlane_b32 s8, v254, 59
	v_readfirstlane_b32 s9, v170
	s_xor_b32 s8, s8, 15
	s_lshr_b32 s15, s9, 6
	s_mul_i32 s15, s15, 3
	s_lshr_b32 s15, 0x54e8f8, s15
	s_and_b32 s15, s15, 7
	s_lshl_b32 s15, s15, 5
	s_lshl_b32 s14, s8, 8
	s_andn2_b32 s15, s15, 31
	s_add_i32 s15, s15, s14
	v_or_b32_e32 v192, s15, v145
	v_ashrrev_i32_e32 v193, 31, v192
	v_writelane_b32 v254, s16, 60
	v_lshl_add_u64 v[0:1], v[192:193], 0, s[94:95]
	v_mov_b32_e32 v232, 0
	v_writelane_b32 v254, s17, 61
	v_mov_b64_e32 v[2:3], s[16:17]
	s_movk_i32 s16, 0x1200
	v_mad_u64_u32 v[2:3], s[14:15], v0, s16, v[2:3]
	v_mad_i32_i24 v3, v1, s16, v3
	v_lshl_add_u64 v[2:3], v[2:3], 0, v[164:165]
	global_load_dwordx4 v[64:67], v[2:3], off
	global_load_dwordx4 v[68:71], v[2:3], off offset:32
	global_load_dwordx4 v[72:75], v[2:3], off offset:64
	global_load_dwordx4 v[76:79], v[2:3], off offset:96
	v_lshl_add_u64 v[2:3], v[192:193], 2, s[22:23]
	global_load_dword v193, v[2:3], off
	v_mov_b64_e32 v[2:3], s[20:21]
	v_mad_u64_u32 v[2:3], s[14:15], v0, s16, v[2:3]
	v_mad_i32_i24 v3, v1, s16, v3
	v_lshl_add_u64 v[0:1], v[2:3], 0, v[164:165]
	global_load_dwordx4 v[2:5], v[0:1], off
	s_mul_i32 s14, s94, 0x900
	s_lshl_b32 s16, s14, 1
	s_add_u32 s14, s20, s16
	s_addc_u32 s15, s21, 0
	s_add_u32 s18, s12, s16
	s_addc_u32 s19, s13, 0
	s_waitcnt vmcnt(12)
	v_lshl_add_u64 v[174:175], s[14:15], 0, v[160:161]
	v_lshl_add_u64 v[176:177], s[18:19], 0, v[160:161]
	v_writelane_b32 v254, s22, 62
	v_mov_b32_e32 v233, 0
	s_waitcnt vmcnt(5)
	v_and_b32_e32 v8, 0xffff0000, v64
	v_lshlrev_b32_e32 v6, 16, v64
	s_waitcnt vmcnt(4)
	v_and_b32_e32 v9, 0xffff0000, v68
	v_writelane_b32 v254, s23, 63
	v_lshl_add_u64 v[178:179], v[170:171], 2, s[22:23]
	s_waitcnt vmcnt(0)
	v_lshlrev_b32_e32 v7, 16, v2
	v_and_b32_e32 v2, 0xffff0000, v2
	v_mul_f32_e32 v2, v8, v2
	v_fmac_f32_e32 v2, v6, v7
	v_lshlrev_b32_e32 v6, 16, v65
	v_lshlrev_b32_e32 v7, 16, v3
	v_fmac_f32_e32 v2, v6, v7
	v_and_b32_e32 v6, 0xffff0000, v65
	v_and_b32_e32 v3, 0xffff0000, v3
	v_fmac_f32_e32 v2, v6, v3
	v_lshlrev_b32_e32 v3, 16, v66
	v_lshlrev_b32_e32 v6, 16, v4
	v_fmac_f32_e32 v2, v3, v6
	v_and_b32_e32 v3, 0xffff0000, v66
	v_and_b32_e32 v4, 0xffff0000, v4
	v_fmac_f32_e32 v2, v3, v4
	v_lshlrev_b32_e32 v3, 16, v67
	v_lshlrev_b32_e32 v4, 16, v5
	v_fmac_f32_e32 v2, v3, v4
	v_and_b32_e32 v3, 0xffff0000, v67
	v_and_b32_e32 v4, 0xffff0000, v5
	v_fmac_f32_e32 v2, v3, v4
	v_add_f32_e32 v6, 0, v2
	global_load_dwordx4 v[2:5], v[0:1], off offset:32
	v_lshlrev_b32_e32 v7, 16, v68
	s_waitcnt vmcnt(0)
	v_lshlrev_b32_e32 v8, 16, v2
	v_and_b32_e32 v2, 0xffff0000, v2
	v_mul_f32_e32 v2, v9, v2
	v_fmac_f32_e32 v2, v7, v8
	v_lshlrev_b32_e32 v7, 16, v69
	v_lshlrev_b32_e32 v8, 16, v3
	v_fmac_f32_e32 v2, v7, v8
	v_and_b32_e32 v7, 0xffff0000, v69
	v_and_b32_e32 v3, 0xffff0000, v3
	v_fmac_f32_e32 v2, v7, v3
	v_lshlrev_b32_e32 v3, 16, v70
	v_lshlrev_b32_e32 v7, 16, v4
	v_fmac_f32_e32 v2, v3, v7
	v_and_b32_e32 v3, 0xffff0000, v70
	v_and_b32_e32 v4, 0xffff0000, v4
	v_fmac_f32_e32 v2, v3, v4
	v_lshlrev_b32_e32 v3, 16, v71
	v_lshlrev_b32_e32 v4, 16, v5
	v_fmac_f32_e32 v2, v3, v4
	v_and_b32_e32 v3, 0xffff0000, v71
	v_and_b32_e32 v4, 0xffff0000, v5
	v_fmac_f32_e32 v2, v3, v4
	v_add_f32_e32 v6, v6, v2
	global_load_dwordx4 v[2:5], v[0:1], off offset:64
	v_and_b32_e32 v9, 0xffff0000, v72
	v_lshlrev_b32_e32 v7, 16, v72
	s_waitcnt vmcnt(0)
	v_lshlrev_b32_e32 v8, 16, v2
	v_and_b32_e32 v2, 0xffff0000, v2
	v_mul_f32_e32 v2, v9, v2
	v_fmac_f32_e32 v2, v7, v8
	v_lshlrev_b32_e32 v7, 16, v73
	v_lshlrev_b32_e32 v8, 16, v3
	v_fmac_f32_e32 v2, v7, v8
	v_and_b32_e32 v7, 0xffff0000, v73
	v_and_b32_e32 v3, 0xffff0000, v3
	v_fmac_f32_e32 v2, v7, v3
	v_lshlrev_b32_e32 v3, 16, v74
	v_lshlrev_b32_e32 v7, 16, v4
	v_fmac_f32_e32 v2, v3, v7
	v_and_b32_e32 v3, 0xffff0000, v74
	v_and_b32_e32 v4, 0xffff0000, v4
	v_fmac_f32_e32 v2, v3, v4
	v_lshlrev_b32_e32 v3, 16, v75
	v_lshlrev_b32_e32 v4, 16, v5
	v_fmac_f32_e32 v2, v3, v4
	v_and_b32_e32 v3, 0xffff0000, v75
	v_and_b32_e32 v4, 0xffff0000, v5
	v_fmac_f32_e32 v2, v3, v4
	v_add_f32_e32 v4, v6, v2
	global_load_dwordx4 v[0:3], v[0:1], off offset:96
	v_and_b32_e32 v7, 0xffff0000, v76
	v_lshlrev_b32_e32 v5, 16, v76
	s_waitcnt vmcnt(0)
	v_lshlrev_b32_e32 v6, 16, v0
	v_and_b32_e32 v0, 0xffff0000, v0
	v_mul_f32_e32 v0, v7, v0
	v_fmac_f32_e32 v0, v5, v6
	v_lshlrev_b32_e32 v5, 16, v77
	v_lshlrev_b32_e32 v6, 16, v1
	v_fmac_f32_e32 v0, v5, v6
	v_and_b32_e32 v5, 0xffff0000, v77
	v_and_b32_e32 v1, 0xffff0000, v1
	v_fmac_f32_e32 v0, v5, v1
	v_lshlrev_b32_e32 v1, 16, v78
	v_lshlrev_b32_e32 v5, 16, v2
	v_fmac_f32_e32 v0, v1, v5
	v_and_b32_e32 v1, 0xffff0000, v78
	v_and_b32_e32 v2, 0xffff0000, v2
	v_fmac_f32_e32 v0, v1, v2
	v_lshlrev_b32_e32 v1, 16, v79
	v_lshlrev_b32_e32 v2, 16, v3
	v_fmac_f32_e32 v0, v1, v2
	v_and_b32_e32 v1, 0xffff0000, v79
	v_and_b32_e32 v2, 0xffff0000, v3
	v_fmac_f32_e32 v0, v1, v2
	v_add_f32_e32 v16, v4, v0
	global_load_dwordx4 v[0:3], v[174:175], off
	global_load_dwordx4 v[4:7], v[176:177], off
	v_mov_b32_e32 v17, v16
	s_nop 1
	v_permlane32_swap_b32_e32 v16, v17
	s_and_saveexec_b64 s[14:15], s[10:11]
	s_cbranch_execz .LBB0_256
	global_load_dword v233, v[178:179], off

; #define ATT_BAR() do { asm volatile("s_waitcnt lgkmcnt(0)" ::: "memory"); __builtin_amdgcn_s_barrier(); asm volatile("" ::: "memory"); } while (0)
; template <int DQK, int DV, int MODE>
; __device__ __forceinline__ void attn_unit(LAS unsigned char* lds, const AttnP& P, size_t rowbase, int qb, const int tid, const int pm) {
;     ...
;     ATT_LOAD(A, 0); ATT_LOAD(B, 1);
;     ATT_STORE(A, 0); ATT_STORE(B, 1);
;     ATT_LOAD(A, 2); ATT_LOAD(B, 3);
;     ATT_BAR();
;     for (int kt = 0; kt < NT; kt += 2) {
;         const int sb = (kt & 2);
;         const bool two_ = (kt + 1 <= ktlast);
;         if (kt <= ktlast && pm != 1) ATT_COMPUTE(kt, sb, true, (KPF2 && MODE == 0 && two_));
.LBB0_266:
	s_or_b64 exec, exec, s[14:15]
	s_lshl_b32 s97, s8, 2
	s_lshr_b32 s9, s9, 6
	s_mul_i32 s9, s9, 3
	s_lshr_b32 s9, 0x54e8f8, s9
	s_and_b32 s9, s9, 7
	s_lshr_b32 s9, s9, 1
	s_add_i32 s9, s9, s97
	v_lshl_or_b32 v0, s9, 6, v218
	v_or_b32_e32 v1, 32, v0
	v_cmp_gt_i32_e64 s[16:17], v1, v192
	v_or_b32_e32 v1, 33, v0
	v_cmp_gt_i32_e64 s[20:21], v1, v192
	v_or_b32_e32 v1, 2, v0
	v_cmp_gt_i32_e64 s[22:23], v1, v192
	v_or_b32_e32 v1, 34, v0
	v_cmp_gt_i32_e64 s[24:25], v1, v192
	v_or_b32_e32 v1, 3, v0
	v_cmp_gt_i32_e64 s[26:27], v1, v192
	v_or_b32_e32 v1, 35, v0
	v_cmp_gt_i32_e64 s[28:29], v1, v192
	v_or_b32_e32 v1, 8, v0
	v_cmp_gt_i32_e64 s[30:31], v1, v192
	v_or_b32_e32 v1, 40, v0
	v_cmp_gt_i32_e64 s[34:35], v1, v192
	v_or_b32_e32 v1, 9, v0
	v_cmp_gt_i32_e64 s[36:37], v1, v192
	v_or_b32_e32 v1, 41, v0
	v_cmp_gt_i32_e64 s[38:39], v1, v192
	v_or_b32_e32 v1, 10, v0
	v_cmp_gt_i32_e64 s[40:41], v1, v192
	v_or_b32_e32 v1, 42, v0
	v_cmp_gt_i32_e64 s[42:43], v1, v192
	v_or_b32_e32 v1, 11, v0
	v_cmp_gt_i32_e64 s[44:45], v1, v192
	v_or_b32_e32 v1, 43, v0
	v_cmp_gt_i32_e64 s[46:47], v1, v192
	v_or_b32_e32 v1, 16, v0
	v_cmp_gt_i32_e64 s[48:49], v1, v192
	v_or_b32_e32 v1, 48, v0
	v_cmp_gt_i32_e64 s[50:51], v1, v192
	v_or_b32_e32 v1, 17, v0
	v_cmp_gt_i32_e64 s[52:53], v1, v192
	v_or_b32_e32 v1, 49, v0
	v_cmp_gt_i32_e64 s[54:55], v1, v192
	v_or_b32_e32 v1, 18, v0
	v_cmp_gt_i32_e64 s[56:57], v1, v192
	v_or_b32_e32 v1, 50, v0
	v_cmp_gt_i32_e64 s[58:59], v1, v192
	v_or_b32_e32 v1, 19, v0
	v_cmp_gt_i32_e64 s[60:61], v1, v192
	v_or_b32_e32 v1, 51, v0
	v_cmp_gt_i32_e64 s[62:63], v1, v192
	v_or_b32_e32 v1, 24, v0
	v_cmp_gt_i32_e64 s[64:65], v1, v192
	v_or_b32_e32 v1, 56, v0
	v_cmp_gt_i32_e64 s[66:67], v1, v192
	v_or_b32_e32 v1, 25, v0
	v_cmp_gt_i32_e64 s[68:69], v1, v192
	v_or_b32_e32 v1, 57, v0
	s_bfe_u32 s12, s83, 0x30006
	s_lshl_b32 s13, s83, 4
	v_cmp_gt_i32_e64 s[70:71], v1, v192
	v_or_b32_e32 v1, 26, v0
	s_mul_i32 s12, s12, 0x1200000
	s_and_b32 s13, s13, 0x380
	s_waitcnt lgkmcnt(0)
	s_barrier
	v_cmp_gt_i32_e64 s[72:73], v1, v192
	v_or_b32_e32 v1, 58, v0
	s_or_b32 s12, s13, s12
	s_mov_b32 s13, s95
	v_cmp_gt_i32_e64 s[14:15], v0, v192
	v_cmp_lt_i32_e64 s[18:19], v0, v192
	v_cmp_gt_i32_e64 s[74:75], v1, v192
	v_or_b32_e32 v1, 27, v0
	v_or_b32_e32 v0, 59, v0
	v_lshl_add_u64 v[162:163], s[80:81], 2, v[158:159]
	v_lshl_add_u64 v[172:173], s[12:13], 0, v[160:161]
	s_add_i32 s8, s97, 4
	v_add_f32_e32 v234, v16, v17
	v_cmp_gt_i32_e64 s[76:77], v1, v192
	v_cmp_gt_i32_e64 s[78:79], v0, v192
	s_add_i32 s83, s9, -1
	s_mov_b32 s86, 0
	v_mov_b32_e32 v16, v165
	v_mov_b32_e32 v17, v165
	v_mov_b32_e32 v18, v165
	v_mov_b32_e32 v19, v165
	v_mov_b32_e32 v20, v165
	v_mov_b32_e32 v21, v165
	v_mov_b32_e32 v22, v165
	v_mov_b32_e32 v23, v165
	v_mov_b32_e32 v24, v165
	v_mov_b32_e32 v25, v165
	v_mov_b32_e32 v26, v165
	v_mov_b32_e32 v27, v165
	v_mov_b32_e32 v28, v165
	v_mov_b32_e32 v29, v165
	v_mov_b32_e32 v30, v165
	v_mov_b32_e32 v31, v165
	v_mov_b32_e32 v0, v165
	v_mov_b32_e32 v1, v165
	v_mov_b32_e32 v2, v165
	v_mov_b32_e32 v3, v165
	v_mov_b32_e32 v4, v165
	v_mov_b32_e32 v5, v165
	v_mov_b32_e32 v6, v165
	v_mov_b32_e32 v7, v165
	s_waitcnt vmcnt(5)
	v_mov_b32_e32 v8, v165
	v_mov_b32_e32 v9, v165
	v_mov_b32_e32 v10, v165
	v_mov_b32_e32 v11, v165
	s_waitcnt vmcnt(4)
	v_mov_b32_e32 v12, v165
	v_mov_b32_e32 v13, v165
	v_mov_b32_e32 v14, v165
	v_mov_b32_e32 v15, v165
	v_mov_b32_e32 v235, 0
	v_mov_b64_e32 v[194:195], v[172:173]
	v_mov_b64_e32 v[196:197], v[162:163]

; template <int DQK, int DV, int MODE>
; __device__ __forceinline__ void attn_unit(LAS unsigned char* lds, const AttnP& P, size_t rowbase, int qb, const int tid, const int pm) {
;     ...
;     float ltot; { auto rr_ = __builtin_amdgcn_permlane32_swap(__float_as_uint(lrun), __float_as_uint(lrun), false, false); ltot = __uint_as_float(rr_[0]) + __uint_as_float(rr_[1]); }
;     const float inv = 1.0f / ltot;
;     int qpe_ = qpos; asm volatile("" : "+v"(qpe_));
;     bf16_t* orow = P.O + (rowbase + qpe_) * (size_t)P.ldo + 8 * hi;
;     if (MODE == 2 && P.Oprev != nullptr) {
;         const bf16_t* prow = P.Oprev + (rowbase + qpe_) * (size_t)P.ldo + 8 * hi;
;         f32x4 cv[NDB][2][2]; float ss = 0.f;
; #pragma unroll
;         for (int db = 0; db < NDB; ++db)
; #pragma unroll
;             for (int a = 0; a < 4; a += 2) {
;                 const unsigned x0 = cvt_pk_bf16(o[db][4 * a] * inv, o[db][4 * a + 1] * inv), x1 = cvt_pk_bf16(o[db][4 * a + 2] * inv, o[db][4 * a + 3] * inv);
;                 const unsigned y0 = cvt_pk_bf16(o[db][4 * a + 4] * inv, o[db][4 * a + 5] * inv), y1 = cvt_pk_bf16(o[db][4 * a + 6] * inv, o[db][4 * a + 7] * inv);
;                 const auto s0_ = __builtin_amdgcn_permlane32_swap(x0, y0, false, false);
;                 const auto s1_ = __builtin_amdgcn_permlane32_swap(x1, y1, false, false);
;                 const u32x4 w1 = *(const u32x4*)(prow + db * 32 + a * 8);
;                 const f32x4 d0 = (f32x4){bf_lo(w1.x) - P.lam * bf_lo(s0_[0]), bf_hi(w1.x) - P.lam * bf_hi(s0_[0]), bf_lo(w1.y) - P.lam * bf_lo(s1_[0]), bf_hi(w1.y) - P.lam * bf_hi(s1_[0])};
;                 const f32x4 d1 = (f32x4){bf_lo(w1.z) - P.lam * bf_lo(s0_[1]), bf_hi(w1.z) - P.lam * bf_hi(s0_[1]), bf_lo(w1.w) - P.lam * bf_lo(s1_[1]), bf_hi(w1.w) - P.lam * bf_hi(s1_[1])};
;                 cv[db][a >> 1][0] = d0; cv[db][a >> 1][1] = d1;
;                 ss += (d0[0] * d0[0] + d0[1] * d0[1]) + (d0[2] * d0[2] + d0[3] * d0[3]) + (d1[0] * d1[0] + d1[1] * d1[1]) + (d1[2] * d1[2] + d1[3] * d1[3]);
;             }
;         { auto rr_ = __builtin_amdgcn_permlane32_swap(__float_as_uint(ss), __float_as_uint(ss), false, false); ss = __uint_as_float(rr_[0]) + __uint_as_float(rr_[1]); }
;         const float rs = rsqrtf(ss * (1.0f / 128.0f) + RMS_EPS) * P.osc;
;         const float* sgp = P.subln + 8 * hi;
; #pragma unroll
;         for (int db = 0; db < NDB; ++db)
.LBB0_295:
	v_mov_b32_e32 v32, v235
	v_readlane_b32 s8, v255, 0
	s_nop 0
	v_permlane32_swap_b32_e32 v235, v32
	s_lshl_b32 s8, s8, 1
	v_add_f32_e32 v32, v235, v32
	s_add_u32 s12, s88, s8
	v_div_scale_f32 v33, s[8:9], v32, v32, 1.0
	v_rcp_f32_e32 v34, v33
	s_waitcnt lgkmcnt(0)
	s_barrier
	v_fma_f32 v35, -v33, v34, 1.0
	v_fmac_f32_e32 v34, v35, v34
	v_div_scale_f32 v35, vcc, 1.0, v32, 1.0
	v_mul_f32_e32 v36, v35, v34
	v_fma_f32 v37, -v33, v36, v35
	v_fmac_f32_e32 v36, v37, v34
	v_fma_f32 v33, -v33, v36, v35
	v_div_fmas_f32 v33, v33, v34, v36
	v_div_fixup_f32 v34, v33, v32, 1.0
	v_mul_f32_e32 v16, v16, v34
	v_mul_f32_e32 v17, v17, v34
	v_cvt_pk_bf16_f32 v16, v16, v17
	v_mul_f32_e32 v17, v18, v34
	v_ashrrev_i32_e32 v193, 31, v192
	v_mul_f32_e32 v18, v19, v34
	v_lshl_add_u64 v[32:33], v[192:193], 0, s[94:95]
	v_cvt_pk_bf16_f32 v17, v17, v18
	v_mul_f32_e32 v18, v20, v34
	v_mul_f32_e32 v19, v21, v34
	s_addc_u32 s13, s89, 0
	v_lshlrev_b64 v[32:33], 11, v[32:33]
	v_cvt_pk_bf16_f32 v18, v18, v19
	v_mul_f32_e32 v19, v22, v34
	v_writelane_b32 v255, s12, 0
	v_mul_f32_e32 v20, v23, v34
	v_cvt_pk_bf16_f32 v19, v19, v20
	v_permlane32_swap_b32_e32 v16, v18
	v_lshl_add_u64 v[32:33], s[12:13], 0, v[32:33]
	v_lshl_add_u64 v[32:33], v[32:33], 0, v[164:165]
	v_permlane32_swap_b32_e32 v17, v19
	global_store_dwordx4 v[32:33], v[16:19], off
	v_mul_f32_e32 v20, v31, v34
	v_mul_f32_e32 v0, v0, v34
	v_mul_f32_e32 v16, v24, v34
	v_mul_f32_e32 v17, v25, v34
	v_cvt_pk_bf16_f32 v16, v16, v17
	v_mul_f32_e32 v17, v26, v34
	v_mul_f32_e32 v18, v27, v34
	v_cvt_pk_bf16_f32 v17, v17, v18
	v_mul_f32_e32 v18, v28, v34
	v_mul_f32_e32 v19, v29, v34
	v_cvt_pk_bf16_f32 v18, v18, v19
	v_mul_f32_e32 v19, v30, v34
	v_cvt_pk_bf16_f32 v19, v19, v20
	v_permlane32_swap_b32_e32 v16, v18
	s_nop 0
	v_permlane32_swap_b32_e32 v17, v19
	v_mul_f32_e32 v1, v1, v34
	global_store_dwordx4 v[32:33], v[16:19], off offset:32
	v_cvt_pk_bf16_f32 v0, v0, v1
	v_mul_f32_e32 v1, v2, v34
	v_mul_f32_e32 v2, v3, v34
	v_cvt_pk_bf16_f32 v1, v1, v2
	v_mul_f32_e32 v2, v4, v34
	v_mul_f32_e32 v3, v5, v34
	v_cvt_pk_bf16_f32 v2, v2, v3
	v_mul_f32_e32 v3, v6, v34
	v_mul_f32_e32 v4, v7, v34
	v_cvt_pk_bf16_f32 v3, v3, v4
	v_permlane32_swap_b32_e32 v0, v2
	v_permlane32_swap_b32_e32 v1, v3
	global_store_dwordx4 v[32:33], v[0:3], off offset:64
	v_readfirstlane_b32 s9, v170
	v_writelane_b32 v255, s13, 1
	v_mul_f32_e32 v0, v8, v34
	v_mul_f32_e32 v1, v9, v34
	v_cvt_pk_bf16_f32 v0, v0, v1
	v_mul_f32_e32 v1, v10, v34
	v_mul_f32_e32 v2, v11, v34
	v_readlane_b32 s8, v254, 59
	s_lshr_b32 s12, s9, 6
	s_mul_i32 s12, s12, 3
	s_lshr_b32 s12, 0x54e8f8, s12
	s_and_b32 s12, s12, 7
	s_lshl_b32 s12, s12, 5
	v_cvt_pk_bf16_f32 v1, v1, v2
	v_mul_f32_e32 v2, v12, v34
	v_mul_f32_e32 v3, v13, v34
	s_lshl_b32 s8, s8, 8
	s_andn2_b32 s12, s12, 31
	v_cvt_pk_bf16_f32 v2, v2, v3
	v_mul_f32_e32 v3, v14, v34
	s_add_i32 s12, s12, s8
	v_mul_f32_e32 v4, v15, v34
	v_cvt_pk_bf16_f32 v3, v3, v4
	v_or_b32_e32 v192, s12, v145
	v_readlane_b32 s12, v254, 60
	v_permlane32_swap_b32_e32 v0, v2
	v_permlane32_swap_b32_e32 v1, v3
	v_ashrrev_i32_e32 v193, 31, v192
	v_readlane_b32 s13, v254, 61
	global_store_dwordx4 v[32:33], v[0:3], off offset:96
	s_movk_i32 s8, 0x1200
	v_mov_b32_e32 v194, 0
	v_lshl_add_u64 v[0:1], v[192:193], 0, s[94:95]
	v_mov_b64_e32 v[2:3], s[12:13]
	v_mad_u64_u32 v[2:3], s[12:13], v0, s8, v[2:3]
	v_mad_i32_i24 v3, v1, s8, v3
	v_readlane_b32 s12, v254, 62
	v_lshl_add_u64 v[2:3], v[2:3], 0, v[164:165]
	v_readlane_b32 s13, v254, 63
	global_load_dwordx4 v[64:67], v[2:3], off
	global_load_dwordx4 v[68:71], v[2:3], off offset:32
	global_load_dwordx4 v[72:75], v[2:3], off offset:64
	global_load_dwordx4 v[76:79], v[2:3], off offset:96
	v_lshl_add_u64 v[2:3], v[192:193], 2, s[12:13]
	v_readlane_b32 s12, v255, 2
	v_readlane_b32 s13, v255, 3
	global_load_dword v193, v[2:3], off
	s_waitcnt vmcnt(4)
; __device__ __forceinline__ float bf_lo(unsigned w) { return __uint_as_float(w << 16); }
; __device__ __forceinline__ float bf_hi(unsigned w) { return __uint_as_float(w & 0xffff0000u); }
; template <int DQK, int DV, int MODE>
; __device__ __forceinline__ void attn_unit(LAS unsigned char* lds, const AttnP& P, size_t rowbase, int qb, const int tid, const int pm) {
;     ...
;     {
;         const bf16_t* kd = P.K1 + (rowbase + qpos) * (size_t)P.ldk1 + hi * 8;
; #pragma unroll
;         for (int ks = 0; ks < NKS; ++ks) {
;             const u32x4 kv_ = (MODE == 1 && ks >= 4) ? *(const u32x4*)(P.K2 + (rowbase + qpos) * 32 + (ks - 4) * 16 + hi * 8) : *(const u32x4*)(kd + ks * 16);
;             const u32x4 qv_ = __builtin_bit_cast(u32x4, qf[ks]);
;             sdiag += bf_lo(qv_.x) * bf_lo(kv_.x) + bf_hi(qv_.x) * bf_hi(kv_.x) + bf_lo(qv_.y) * bf_lo(kv_.y) + bf_hi(qv_.y) * bf_hi(kv_.y)
;                    + bf_lo(qv_.z) * bf_lo(kv_.z) + bf_hi(qv_.z) * bf_hi(kv_.z) + bf_lo(qv_.w) * bf_lo(kv_.w) + bf_hi(qv_.w) * bf_hi(kv_.w);
;         }
;         auto rr_ = __builtin_amdgcn_permlane32_swap(__float_as_uint(sdiag), __float_as_uint(sdiag), false, false);
;         sdiag = __uint_as_float(rr_[0]) + __uint_as_float(rr_[1]);
	v_and_b32_e32 v8, 0xffff0000, v64
	v_mov_b64_e32 v[2:3], s[12:13]
	v_mad_u64_u32 v[2:3], s[12:13], v0, s8, v[2:3]
	v_mad_i32_i24 v3, v1, s8, v3
	v_lshl_add_u64 v[0:1], v[2:3], 0, v[164:165]
	global_load_dwordx4 v[2:5], v[0:1], off
	v_lshlrev_b32_e32 v6, 16, v64
	s_waitcnt vmcnt(4)
	v_and_b32_e32 v9, 0xffff0000, v68
	s_waitcnt vmcnt(0)
	v_lshlrev_b32_e32 v7, 16, v2
	v_and_b32_e32 v2, 0xffff0000, v2
	v_mul_f32_e32 v2, v8, v2
	v_fmac_f32_e32 v2, v6, v7
	v_lshlrev_b32_e32 v6, 16, v65
	v_lshlrev_b32_e32 v7, 16, v3
	v_fmac_f32_e32 v2, v6, v7
	v_and_b32_e32 v6, 0xffff0000, v65
	v_and_b32_e32 v3, 0xffff0000, v3
	v_fmac_f32_e32 v2, v6, v3
	v_lshlrev_b32_e32 v3, 16, v66
	v_lshlrev_b32_e32 v6, 16, v4
	v_fmac_f32_e32 v2, v3, v6
	v_and_b32_e32 v3, 0xffff0000, v66
	v_and_b32_e32 v4, 0xffff0000, v4
	v_fmac_f32_e32 v2, v3, v4
	v_lshlrev_b32_e32 v3, 16, v67
	v_lshlrev_b32_e32 v4, 16, v5
	v_fmac_f32_e32 v2, v3, v4
	v_and_b32_e32 v3, 0xffff0000, v67
	v_and_b32_e32 v4, 0xffff0000, v5
	v_fmac_f32_e32 v2, v3, v4
	v_add_f32_e32 v6, 0, v2
	global_load_dwordx4 v[2:5], v[0:1], off offset:32
	v_lshlrev_b32_e32 v7, 16, v68
	s_waitcnt vmcnt(0)
	v_lshlrev_b32_e32 v8, 16, v2
	v_and_b32_e32 v2, 0xffff0000, v2
	v_mul_f32_e32 v2, v9, v2
	v_fmac_f32_e32 v2, v7, v8
	v_lshlrev_b32_e32 v7, 16, v69
	v_lshlrev_b32_e32 v8, 16, v3
	v_fmac_f32_e32 v2, v7, v8
	v_and_b32_e32 v7, 0xffff0000, v69
	v_and_b32_e32 v3, 0xffff0000, v3
	v_fmac_f32_e32 v2, v7, v3
	v_lshlrev_b32_e32 v3, 16, v70
	v_lshlrev_b32_e32 v7, 16, v4
	v_fmac_f32_e32 v2, v3, v7
	v_and_b32_e32 v3, 0xffff0000, v70
	v_and_b32_e32 v4, 0xffff0000, v4
	v_fmac_f32_e32 v2, v3, v4
	v_lshlrev_b32_e32 v3, 16, v71
	v_lshlrev_b32_e32 v4, 16, v5
	v_fmac_f32_e32 v2, v3, v4
	v_and_b32_e32 v3, 0xffff0000, v71
	v_and_b32_e32 v4, 0xffff0000, v5
	v_fmac_f32_e32 v2, v3, v4
	v_add_f32_e32 v6, v6, v2
	global_load_dwordx4 v[2:5], v[0:1], off offset:64
	v_and_b32_e32 v9, 0xffff0000, v72
	v_lshlrev_b32_e32 v7, 16, v72
	s_waitcnt vmcnt(0)
	v_lshlrev_b32_e32 v8, 16, v2
	v_and_b32_e32 v2, 0xffff0000, v2
	v_mul_f32_e32 v2, v9, v2
	v_fmac_f32_e32 v2, v7, v8
	v_lshlrev_b32_e32 v7, 16, v73
	v_lshlrev_b32_e32 v8, 16, v3
	v_fmac_f32_e32 v2, v7, v8
	v_and_b32_e32 v7, 0xffff0000, v73
	v_and_b32_e32 v3, 0xffff0000, v3
	v_fmac_f32_e32 v2, v7, v3
	v_lshlrev_b32_e32 v3, 16, v74
	v_lshlrev_b32_e32 v7, 16, v4
	v_fmac_f32_e32 v2, v3, v7
	v_and_b32_e32 v3, 0xffff0000, v74
	v_and_b32_e32 v4, 0xffff0000, v4
	v_fmac_f32_e32 v2, v3, v4
	v_lshlrev_b32_e32 v3, 16, v75
	v_lshlrev_b32_e32 v4, 16, v5
	v_fmac_f32_e32 v2, v3, v4
	v_and_b32_e32 v3, 0xffff0000, v75
	v_and_b32_e32 v4, 0xffff0000, v5
	v_fmac_f32_e32 v2, v3, v4
	v_add_f32_e32 v4, v6, v2
	global_load_dwordx4 v[0:3], v[0:1], off offset:96
	v_and_b32_e32 v7, 0xffff0000, v76
	v_lshlrev_b32_e32 v5, 16, v76
	s_waitcnt vmcnt(0)
	v_lshlrev_b32_e32 v6, 16, v0
	v_and_b32_e32 v0, 0xffff0000, v0
	v_mul_f32_e32 v0, v7, v0
	v_fmac_f32_e32 v0, v5, v6
	v_lshlrev_b32_e32 v5, 16, v77
	v_lshlrev_b32_e32 v6, 16, v1
	v_fmac_f32_e32 v0, v5, v6
	v_and_b32_e32 v5, 0xffff0000, v77
	v_and_b32_e32 v1, 0xffff0000, v1
	v_fmac_f32_e32 v0, v5, v1
	v_lshlrev_b32_e32 v1, 16, v78
	v_lshlrev_b32_e32 v5, 16, v2
	v_fmac_f32_e32 v0, v1, v5
	v_and_b32_e32 v1, 0xffff0000, v78
	v_and_b32_e32 v2, 0xffff0000, v2
	v_fmac_f32_e32 v0, v1, v2
	v_lshlrev_b32_e32 v1, 16, v79
	v_lshlrev_b32_e32 v2, 16, v3
	v_fmac_f32_e32 v0, v1, v2
	v_and_b32_e32 v1, 0xffff0000, v79
	v_and_b32_e32 v2, 0xffff0000, v3
	v_fmac_f32_e32 v0, v1, v2
	v_add_f32_e32 v16, v4, v0
	global_load_dwordx4 v[0:3], v[174:175], off
	global_load_dwordx4 v[4:7], v[176:177], off
	v_mov_b32_e32 v17, v16
	s_nop 1
	v_permlane32_swap_b32_e32 v16, v17
	v_mov_b32_e32 v174, 0
	s_and_saveexec_b64 s[14:15], s[10:11]
	s_cbranch_execz .LBB0_297
	global_load_dword v174, v[178:179], off

; #define ATT_BAR() do { asm volatile("s_waitcnt lgkmcnt(0)" ::: "memory"); __builtin_amdgcn_s_barrier(); asm volatile("" ::: "memory"); } while (0)
; template <int DQK, int DV, int MODE>
; __device__ __forceinline__ void attn_unit(LAS unsigned char* lds, const AttnP& P, size_t rowbase, int qb, const int tid, const int pm) {
;     ...
;     ATT_LOAD(A, 0); ATT_LOAD(B, 1);
;     ATT_STORE(A, 0); ATT_STORE(B, 1);
;     ATT_LOAD(A, 2); ATT_LOAD(B, 3);
;     ATT_BAR();
;     for (int kt = 0; kt < NT; kt += 2) {
;         const int sb = (kt & 2);
;         const bool two_ = (kt + 1 <= ktlast);
;         if (kt <= ktlast && pm != 1) ATT_COMPUTE(kt, sb, true, (KPF2 && MODE == 0 && two_));
.LBB0_307:
	s_or_b64 exec, exec, s[14:15]
	v_readlane_b32 s8, v254, 59
	s_lshl_b32 s8, s8, 2
	s_lshr_b32 s83, s9, 6
	s_mul_i32 s83, s83, 3
	s_lshr_b32 s83, 0x54e8f8, s83
	s_and_b32 s83, s83, 7
	s_lshr_b32 s83, s83, 1
	s_add_i32 s83, s83, s8
	v_lshl_or_b32 v0, s83, 6, v218
	v_or_b32_e32 v1, 32, v0
	v_cmp_gt_i32_e64 s[16:17], v1, v192
	v_or_b32_e32 v1, 33, v0
	v_cmp_gt_i32_e64 s[20:21], v1, v192
	v_or_b32_e32 v1, 2, v0
	v_cmp_gt_i32_e64 s[22:23], v1, v192
	v_or_b32_e32 v1, 34, v0
	v_cmp_gt_i32_e64 s[24:25], v1, v192
	v_or_b32_e32 v1, 3, v0
	v_cmp_gt_i32_e64 s[26:27], v1, v192
	v_or_b32_e32 v1, 35, v0
	v_cmp_gt_i32_e64 s[28:29], v1, v192
	v_or_b32_e32 v1, 8, v0
	v_cmp_gt_i32_e64 s[30:31], v1, v192
	v_or_b32_e32 v1, 40, v0
	v_cmp_gt_i32_e64 s[34:35], v1, v192
	v_or_b32_e32 v1, 9, v0
	v_cmp_gt_i32_e64 s[36:37], v1, v192
	v_or_b32_e32 v1, 41, v0
	v_cmp_gt_i32_e64 s[38:39], v1, v192
	v_or_b32_e32 v1, 10, v0
	v_cmp_gt_i32_e64 s[40:41], v1, v192
	v_or_b32_e32 v1, 42, v0
	v_cmp_gt_i32_e64 s[42:43], v1, v192
	v_or_b32_e32 v1, 11, v0
	v_cmp_gt_i32_e64 s[44:45], v1, v192
	v_or_b32_e32 v1, 43, v0
	v_cmp_gt_i32_e64 s[46:47], v1, v192
	v_or_b32_e32 v1, 16, v0
	v_cmp_gt_i32_e64 s[48:49], v1, v192
	v_or_b32_e32 v1, 48, v0
	v_cmp_gt_i32_e64 s[50:51], v1, v192
	v_or_b32_e32 v1, 17, v0
	v_cmp_gt_i32_e64 s[52:53], v1, v192
	v_or_b32_e32 v1, 49, v0
	v_cmp_gt_i32_e64 s[54:55], v1, v192
	v_or_b32_e32 v1, 18, v0
	v_cmp_gt_i32_e64 s[56:57], v1, v192
	v_or_b32_e32 v1, 50, v0
	v_cmp_gt_i32_e64 s[58:59], v1, v192
	v_or_b32_e32 v1, 19, v0
	v_cmp_gt_i32_e64 s[60:61], v1, v192
	v_or_b32_e32 v1, 51, v0
	v_cmp_gt_i32_e64 s[62:63], v1, v192
	v_or_b32_e32 v1, 24, v0
	v_cmp_gt_i32_e64 s[64:65], v1, v192
	v_or_b32_e32 v1, 56, v0
	v_cmp_gt_i32_e64 s[66:67], v1, v192
	v_or_b32_e32 v1, 25, v0
	v_cmp_gt_i32_e64 s[68:69], v1, v192
	v_or_b32_e32 v1, 57, v0
	v_cmp_gt_i32_e64 s[70:71], v1, v192
	v_or_b32_e32 v1, 26, v0
	s_waitcnt lgkmcnt(0)
	s_barrier
	v_cmp_gt_i32_e64 s[72:73], v1, v192
	v_or_b32_e32 v1, 58, v0
	v_cmp_gt_i32_e64 s[14:15], v0, v192
	v_cmp_lt_i32_e64 s[18:19], v0, v192
	v_cmp_gt_i32_e64 s[74:75], v1, v192
	v_or_b32_e32 v1, 27, v0
	v_or_b32_e32 v0, 59, v0
	s_add_i32 s9, s8, 4
	v_add_f32_e32 v175, v16, v17
	v_cmp_gt_i32_e64 s[76:77], v1, v192
	v_cmp_gt_i32_e64 s[78:79], v0, v192
	s_add_i32 s86, s83, -1
	s_mov_b32 s12, 0
	v_mov_b32_e32 v16, v165
	v_mov_b32_e32 v17, v165
	v_mov_b32_e32 v18, v165
	v_mov_b32_e32 v19, v165
	v_mov_b32_e32 v20, v165
	v_mov_b32_e32 v21, v165
	v_mov_b32_e32 v22, v165
	v_mov_b32_e32 v23, v165
	v_mov_b32_e32 v24, v165
	v_mov_b32_e32 v25, v165
	v_mov_b32_e32 v26, v165
	v_mov_b32_e32 v27, v165
	v_mov_b32_e32 v28, v165
	v_mov_b32_e32 v29, v165
	v_mov_b32_e32 v30, v165
	v_mov_b32_e32 v31, v165
	v_mov_b32_e32 v0, v165
	v_mov_b32_e32 v1, v165
	v_mov_b32_e32 v2, v165
	v_mov_b32_e32 v3, v165
	v_mov_b32_e32 v4, v165
	v_mov_b32_e32 v5, v165
	v_mov_b32_e32 v6, v165
	v_mov_b32_e32 v7, v165
	s_waitcnt vmcnt(5)
	v_mov_b32_e32 v8, v165
	v_mov_b32_e32 v9, v165
	v_mov_b32_e32 v10, v165
	v_mov_b32_e32 v11, v165
	s_waitcnt vmcnt(4)
	v_mov_b32_e32 v12, v165
	v_mov_b32_e32 v13, v165
	v_mov_b32_e32 v14, v165
	v_mov_b32_e32 v15, v165
	v_mov_b32_e32 v176, 0
